# GEMM epilogue rstd cache: a workgroup's tiles in one GEMM phase share the row block, so the per-row rstd values are computed once (first tile), kept in 1 KiB of LDS outside the GEMM buffers and re-rea
# baseline (speedup 1.0000x reference)
; #define PG8_STAGE(bufoff, gbase, voff) do { _Pragma("unroll") for (int _i = 0; _i < 2; ++_i) \
;         __builtin_amdgcn_global_load_lds((const unsigned*)((const char*)(gbase) + (voff)[_i]), (PG8_LAS unsigned*)(lds + (bufoff) + ldsw + _i * 8192), 16, 0, 0); } while (0)
; #define PG8_WAIT_V(n) asm volatile("s_waitcnt vmcnt(" #n ")" ::: "memory")
; #define PG8_BAR __builtin_amdgcn_s_barrier()
; template <class Epi, class Sched, bool ALIGN_EPI = false, bool SP2 = false>
; __device__ __forceinline__ void gemm_phase(PG8_LAS unsigned char* lds, const Gemm g, const Sched& S, const Epi& E) {
;     ...
;     const int tid = tid_, wid = __builtin_amdgcn_readfirstlane(tid >> 6), lane = tid & 63, wr = wid >> 2, wc = wid & 3, fr = lane & 15, fq = lane >> 4;
;     const int K = g.K, nt = K / BK;
;     unsigned voffA[2], voffB[2];
; #pragma unroll
;     for (int i = 0; i < 2; ++i) { int R, C; stage_rc(tid * 16 + i * 8192, R, C); const int Rb = Epi::PERM ? ((R & ~31) + perm32(R & 31)) : R;
;         voffA[i] = (unsigned)(R * K + C) * 2u; voffB[i] = (unsigned)(Rb * K + C) * 2u; }
;     const size_t kstep = (size_t)(BK * 2);
;     const size_t hstep = (size_t)HALF * K * 2;
;     const size_t tstep = 2 * hstep;
;     const unsigned ldsw = (unsigned)wid * 1024u;
;     const int aoff = lds_byte(wr * 64 + fr, fq * 8), boff = lds_byte(wc * 32 + fr, fq * 8);
;     ...
;         PG8_STAGE(PG8_SB(0, 0), cB, voffB); PG8_STAGE(PG8_SB(0, 1), cB + hstep, voffB); PG8_STAGE(PG8_SA(0, 0), cA, voffA); PG8_STAGE(PG8_SA(0, 1), cA + hstep, voffA);
;         if (wr == 1) PG8_BAR;
;         PG8_WAIT_V(2); PG8_BAR;
;         PG8_STAGE(PG8_SB(1, 0), cB + kstep, voffB); PG8_STAGE(PG8_SA(1, 0), cA + kstep, voffA); PG8_STAGE(PG8_SB(1, 1), cB + hstep + kstep, voffB);
;         PG8_WAIT_V(6); PG8_BAR;
.LBB0_3150:
	s_add_u32 s22, s0, 0x8c00000
	s_addc_u32 s23, s1, 0
	s_add_i32 m0, s46, 0x18000
	v_lshl_add_u64 v[2:3], v[2:3], 0, s[92:93]
	s_waitcnt vmcnt(2)
	s_barrier
	global_load_lds_dwordx4 v[2:3], off
	v_lshl_add_u64 v[2:3], v[4:5], 0, s[92:93]
	s_add_i32 m0, s46, 0x1a000
	s_add_i32 s50, s46, 0x8000
	global_load_lds_dwordx4 v[2:3], off
	v_lshl_add_u64 v[2:3], v[10:11], 0, s[92:93]
	s_mov_b32 m0, s50
	s_add_i32 s51, s46, 0xa000
	global_load_lds_dwordx4 v[2:3], off
	v_lshl_add_u64 v[2:3], v[12:13], 0, s[92:93]
	s_mov_b32 m0, s51
	v_bfe_u32 v4, v14, 4, 2
	global_load_lds_dwordx4 v[2:3], off
	s_add_i32 m0, s46, 0x1c000
	v_lshl_add_u64 v[2:3], v[6:7], 0, s[92:93]
	global_load_lds_dwordx4 v[2:3], off
	v_lshl_add_u64 v[2:3], v[8:9], 0, s[92:93]
	s_add_i32 m0, s46, 0x1e000
	s_lshr_b32 s5, s5, 26
	global_load_lds_dwordx4 v[2:3], off
	v_and_b32_e32 v3, 15, v14
	s_add_i32 s5, s4, s5
	v_lshlrev_b32_e32 v2, 4, v4
	v_lshlrev_b32_e32 v5, 2, v14
	s_ashr_i32 s52, s5, 6
	v_lshl_or_b32 v1, s24, 6, v3
	v_lshl_or_b32 v3, v3, 6, v2
	s_lshl_b32 s5, s24, 13
	v_and_b32_e32 v5, 32, v5
	v_bitop3_b32 v6, v3, s5, v5 bitop3:0xde
	s_lshl_b32 s5, s25, 5
	s_and_b32 s5, s5, 0x60
	s_lshl_b32 s24, s5, 7
	s_waitcnt vmcnt(0)
	v_bitop3_b32 v151, v3, s24, v5 bitop3:0xde
	v_mov_b32_e32 v3, v0
	v_lshl_add_u64 v[2:3], s[0:1], 0, v[2:3]
	s_mov_b64 s[0:1], 0x8000000
	v_lshl_add_u64 v[142:143], v[2:3], 0, s[0:1]
	v_add_u32_e32 v2, v20, v18
	s_cmp_gt_i32 s4, 63
	v_add_lshl_u32 v2, v2, v19, 1
	v_mov_b32_e32 v3, v0
	s_waitcnt vmcnt(6)
	s_cselect_b64 s[24:25], -1, 0
	s_add_i32 s53, s52, -2
	v_lshl_add_u64 v[144:145], s[16:17], 0, v[2:3]
	v_add_u32_e32 v2, v17, v15
	s_cmpk_lt_u32 s26, 0x100
	v_add_lshl_u32 v2, v2, v16, 1
	s_cselect_b64 s[26:27], -1, 0
	v_lshl_or_b32 v155, v4, 3, s5
	v_lshl_add_u64 v[146:147], s[16:17], 0, v[2:3]
	s_mov_b32 s54, 0
	v_add_u32_e32 v161, 0, v6
	s_barrier
	s_mov_b32 s32, -1
	s_branch .LBB0_3153

; __device__ __forceinline__ float row_rstd16_coop(const float* ssq, int row, int fq, float inv_n) {
;     const f32x4 a = *(const f32x4*)(ssq + (size_t)row * 16 + fq * 4);
;     float s = (a[0] + a[1]) + (a[2] + a[3]);
;     s += __shfl_xor(s, 16); s += __shfl_xor(s, 32);
;     return __builtin_amdgcn_rsqf(s * inv_n + EPS);
; }
;     __device__ __forceinline__ void operator()(const f32x4 (&acc)[2][2][4][2], const Unit& u, int wr, int wc, int fr, int fq) const {
;         const int row0 = u.pm * BM + wr * 64 + fr, col0 = u.pn * BM + wc * 32 + 8 * fq;
;         float rsv[2][4];
; #pragma unroll
;         for (int ai = 0; ai < 2; ++ai) {
; #pragma unroll
;             for (int m = 0; m < 4; ++m) rsv[ai][m] = row_rstd16_coop(ssq, row0 + ai * HALF + m * 16, fq, 1.0f / 1024.0f);
;         }
; #pragma unroll
;         for (int ai = 0; ai < 2; ++ai)
; #pragma unroll
;             for (int m = 0; m < 4; ++m) {
;                 const int row = row0 + ai * HALF + m * 16;
;                 const float rs = rsv[ai][m];
;                 bf16_t* rowp = H + (size_t)row * ldh + (col0 >> 1);
; #pragma unroll
;                 for (int bj = 0; bj < 2; ++bj) {
;                     const f32x4 v0 = acc[ai][bj][m][0] * rs, v1 = acc[ai][bj][m][1] * rs;
.LBB0_3168:
	s_cmp_eq_u32 s58, s32
	s_cbranch_scc1 .Lmy_rs_cached_0
	s_mov_b32 s32, s58
	v_lshlrev_b32_e32 v212, 2, v1
	v_add_u32_e32 v212, 0x21000, v212
	v_lshl_add_u32 v156, s58, 8, v1
	v_ashrrev_i32_e32 v157, 31, v156
	v_lshlrev_b64 v[130:131], 6, v[156:157]
	v_lshl_add_u64 v[130:131], v[142:143], 0, v[130:131]
	global_load_dwordx4 v[182:185], v[130:131], off offset:1024
	global_load_dwordx4 v[186:189], v[130:131], off offset:2048
	global_load_dwordx4 v[190:193], v[130:131], off offset:3072
	v_add_co_u32_e32 v210, vcc, 0x2000, v130
	s_nop 1
	v_addc_co_u32_e32 v211, vcc, 0, v131, vcc
	global_load_dwordx4 v[194:197], v[210:211], off
	global_load_dwordx4 v[198:201], v[210:211], off offset:1024
	global_load_dwordx4 v[202:205], v[210:211], off offset:2048
	global_load_dwordx4 v[206:209], v[210:211], off offset:3072
	global_load_dwordx4 v[130:133], v[130:131], off
	v_or_b32_e32 v174, 16, v156
	v_ashrrev_i32_e32 v175, 31, v174
	v_or_b32_e32 v170, 32, v156
	v_ashrrev_i32_e32 v171, 31, v170
	v_or_b32_e32 v166, 48, v156
	v_ashrrev_i32_e32 v167, 31, v166
	v_add_u32_e32 v162, 0x80, v156
	v_ashrrev_i32_e32 v163, 31, v162
	v_add_u32_e32 v158, 0x90, v156
	v_ashrrev_i32_e32 v159, 31, v158
	v_add_u32_e32 v152, 0xa0, v156
	v_ashrrev_i32_e32 v153, 31, v152
	s_and_b64 vcc, exec, s[4:5]
	s_waitcnt vmcnt(0)
	v_mov_b32_e32 v148, v131
	v_mov_b32_e32 v149, v132
	v_mov_b32_e32 v131, v133
	v_pk_add_f32 v[130:131], v[148:149], v[130:131]
	s_nop 0
	v_add_f32_e32 v130, v130, v131
	v_mov_b32_e32 v131, v130
	s_nop 1
	v_permlane16_swap_b32 v131, v130
	s_waitcnt lgkmcnt(0)
	v_add_f32_e32 v130, v130, v131
	v_mov_b32_e32 v131, v130
	s_nop 1
	v_permlane32_swap_b32 v131, v130
	s_waitcnt lgkmcnt(0)
	v_add_f32_e32 v130, v130, v131
	v_fmamk_f32 v130, v130, 0x3a800000, v231
	v_rsq_f32_e32 v176, v130
	s_nop 1
	ds_write_b32 v212, v176
	s_nop 1
	v_pk_mul_f32 v[122:123], v[122:123], v[176:177] op_sel_hi:[1,0]
	v_pk_mul_f32 v[124:125], v[124:125], v[176:177] op_sel_hi:[1,0]
	v_pk_mul_f32 v[126:127], v[126:127], v[176:177] op_sel_hi:[1,0]
	v_pk_mul_f32 v[128:129], v[128:129], v[176:177] op_sel_hi:[1,0]
	v_pk_mul_f32 v[118:119], v[118:119], v[176:177] op_sel_hi:[1,0]
	v_pk_mul_f32 v[120:121], v[120:121], v[176:177] op_sel_hi:[1,0]
	v_pk_mul_f32 v[114:115], v[114:115], v[176:177] op_sel_hi:[1,0]
	v_pk_mul_f32 v[116:117], v[116:117], v[176:177] op_sel_hi:[1,0]
	v_add_f32_e32 v130, v183, v182
	v_add_f32_e32 v131, v184, v185
	s_nop 0
	v_add_f32_e32 v130, v130, v131
	v_mov_b32_e32 v131, v130
	s_nop 1
	v_permlane16_swap_b32 v131, v130
	s_waitcnt lgkmcnt(0)
	v_add_f32_e32 v130, v130, v131
	v_mov_b32_e32 v131, v130
	s_nop 1
	v_permlane32_swap_b32 v131, v130
	s_waitcnt lgkmcnt(0)
	v_add_f32_e32 v130, v130, v131
	v_fmamk_f32 v130, v130, 0x3a800000, v231
	v_rsq_f32_e32 v172, v130
	s_nop 1
	ds_write_b32 v212, v172 offset:64
	s_nop 1
	v_pk_mul_f32 v[110:111], v[110:111], v[172:173] op_sel_hi:[1,0]
	v_pk_mul_f32 v[112:113], v[112:113], v[172:173] op_sel_hi:[1,0]
	v_pk_mul_f32 v[106:107], v[106:107], v[172:173] op_sel_hi:[1,0]
	v_pk_mul_f32 v[108:109], v[108:109], v[172:173] op_sel_hi:[1,0]
	v_pk_mul_f32 v[102:103], v[102:103], v[172:173] op_sel_hi:[1,0]
	v_pk_mul_f32 v[104:105], v[104:105], v[172:173] op_sel_hi:[1,0]
	v_pk_mul_f32 v[98:99], v[98:99], v[172:173] op_sel_hi:[1,0]
	v_pk_mul_f32 v[100:101], v[100:101], v[172:173] op_sel_hi:[1,0]
	v_add_f32_e32 v130, v187, v186
	v_add_f32_e32 v131, v188, v189
	s_nop 0
	v_add_f32_e32 v130, v130, v131
	v_mov_b32_e32 v131, v130
	s_nop 1
	v_permlane16_swap_b32 v131, v130
	s_waitcnt lgkmcnt(0)
	v_add_f32_e32 v130, v130, v131
	v_mov_b32_e32 v131, v130
	s_nop 1
	v_permlane32_swap_b32 v131, v130
	s_waitcnt lgkmcnt(0)
	v_add_f32_e32 v130, v130, v131
	v_fmamk_f32 v130, v130, 0x3a800000, v231
	v_rsq_f32_e32 v168, v130
	s_nop 1
	ds_write_b32 v212, v168 offset:128
	s_nop 1
	v_pk_mul_f32 v[94:95], v[94:95], v[168:169] op_sel_hi:[1,0]
	v_pk_mul_f32 v[96:97], v[96:97], v[168:169] op_sel_hi:[1,0]
	v_pk_mul_f32 v[90:91], v[90:91], v[168:169] op_sel_hi:[1,0]
	v_pk_mul_f32 v[92:93], v[92:93], v[168:169] op_sel_hi:[1,0]
	v_pk_mul_f32 v[86:87], v[86:87], v[168:169] op_sel_hi:[1,0]
	v_pk_mul_f32 v[88:89], v[88:89], v[168:169] op_sel_hi:[1,0]
	v_pk_mul_f32 v[82:83], v[82:83], v[168:169] op_sel_hi:[1,0]
	v_pk_mul_f32 v[84:85], v[84:85], v[168:169] op_sel_hi:[1,0]
	v_add_f32_e32 v130, v191, v190
	v_add_f32_e32 v131, v192, v193
	s_nop 0
	v_add_f32_e32 v130, v130, v131
	v_mov_b32_e32 v131, v130
	s_nop 1
	v_permlane16_swap_b32 v131, v130
	s_waitcnt lgkmcnt(0)
	v_add_f32_e32 v130, v130, v131
	v_mov_b32_e32 v131, v130
	s_nop 1
	v_permlane32_swap_b32 v131, v130
	s_waitcnt lgkmcnt(0)
	v_add_f32_e32 v130, v130, v131
	v_fmamk_f32 v130, v130, 0x3a800000, v231
	v_rsq_f32_e32 v164, v130
	s_nop 1
	ds_write_b32 v212, v164 offset:192
	s_nop 1
	v_pk_mul_f32 v[78:79], v[78:79], v[164:165] op_sel_hi:[1,0]
	v_pk_mul_f32 v[80:81], v[80:81], v[164:165] op_sel_hi:[1,0]
	v_pk_mul_f32 v[74:75], v[74:75], v[164:165] op_sel_hi:[1,0]
	v_pk_mul_f32 v[76:77], v[76:77], v[164:165] op_sel_hi:[1,0]
	v_pk_mul_f32 v[70:71], v[70:71], v[164:165] op_sel_hi:[1,0]
	v_pk_mul_f32 v[72:73], v[72:73], v[164:165] op_sel_hi:[1,0]
	v_pk_mul_f32 v[66:67], v[66:67], v[164:165] op_sel_hi:[1,0]
	v_pk_mul_f32 v[68:69], v[68:69], v[164:165] op_sel_hi:[1,0]
	v_add_f32_e32 v130, v195, v194
	v_add_f32_e32 v131, v196, v197
	s_nop 0
	v_add_f32_e32 v130, v130, v131
	v_mov_b32_e32 v131, v130
	s_nop 1
	v_permlane16_swap_b32 v131, v130
	s_waitcnt lgkmcnt(0)
	v_add_f32_e32 v130, v130, v131
	v_mov_b32_e32 v131, v130
	s_nop 1
	v_permlane32_swap_b32 v131, v130
	s_waitcnt lgkmcnt(0)
; __device__ __forceinline__ float row_rstd16_coop(const float* ssq, int row, int fq, float inv_n) {
;     const f32x4 a = *(const f32x4*)(ssq + (size_t)row * 16 + fq * 4);
;     float s = (a[0] + a[1]) + (a[2] + a[3]);
;     s += __shfl_xor(s, 16); s += __shfl_xor(s, 32);
;     return __builtin_amdgcn_rsqf(s * inv_n + EPS);
; }
;     __device__ __forceinline__ void operator()(const f32x4 (&acc)[2][2][4][2], const Unit& u, int wr, int wc, int fr, int fq) const {
;         const int row0 = u.pm * BM + wr * 64 + fr, col0 = u.pn * BM + wc * 32 + 8 * fq;
;         float rsv[2][4];
; #pragma unroll
;         for (int ai = 0; ai < 2; ++ai) {
; #pragma unroll
;             for (int m = 0; m < 4; ++m) rsv[ai][m] = row_rstd16_coop(ssq, row0 + ai * HALF + m * 16, fq, 1.0f / 1024.0f);
;         }
; #pragma unroll
;         for (int ai = 0; ai < 2; ++ai)
; #pragma unroll
;             for (int m = 0; m < 4; ++m) {
;                 const int row = row0 + ai * HALF + m * 16;
;                 const float rs = rsv[ai][m];
;                 bf16_t* rowp = H + (size_t)row * ldh + (col0 >> 1);
; #pragma unroll
;                 for (int bj = 0; bj < 2; ++bj) {
;                     const f32x4 v0 = acc[ai][bj][m][0] * rs, v1 = acc[ai][bj][m][1] * rs;
	v_add_f32_e32 v130, v130, v131
	v_fmamk_f32 v130, v130, 0x3a800000, v231
	v_rsq_f32_e32 v160, v130
	s_nop 1
	ds_write_b32 v212, v160 offset:512
	s_nop 1
	v_pk_mul_f32 v[62:63], v[62:63], v[160:161] op_sel_hi:[1,0]
	v_pk_mul_f32 v[64:65], v[64:65], v[160:161] op_sel_hi:[1,0]
	v_pk_mul_f32 v[58:59], v[58:59], v[160:161] op_sel_hi:[1,0]
	v_pk_mul_f32 v[60:61], v[60:61], v[160:161] op_sel_hi:[1,0]
	v_pk_mul_f32 v[54:55], v[54:55], v[160:161] op_sel_hi:[1,0]
	v_pk_mul_f32 v[56:57], v[56:57], v[160:161] op_sel_hi:[1,0]
	v_pk_mul_f32 v[50:51], v[50:51], v[160:161] op_sel_hi:[1,0]
	v_pk_mul_f32 v[52:53], v[52:53], v[160:161] op_sel_hi:[1,0]
	v_add_f32_e32 v130, v199, v198
	v_add_f32_e32 v131, v200, v201
	s_nop 0
	v_add_f32_e32 v130, v130, v131
	v_mov_b32_e32 v131, v130
	s_nop 1
	v_permlane16_swap_b32 v131, v130
	s_waitcnt lgkmcnt(0)
	v_add_f32_e32 v130, v130, v131
	v_mov_b32_e32 v131, v130
	s_nop 1
	v_permlane32_swap_b32 v131, v130
	s_waitcnt lgkmcnt(0)
	v_add_f32_e32 v130, v130, v131
	v_fmamk_f32 v130, v130, 0x3a800000, v231
	v_rsq_f32_e32 v154, v130
	s_nop 1
	ds_write_b32 v212, v154 offset:576
	s_nop 1
	v_pk_mul_f32 v[46:47], v[46:47], v[154:155] op_sel_hi:[1,0]
	v_pk_mul_f32 v[48:49], v[48:49], v[154:155] op_sel_hi:[1,0]
	v_pk_mul_f32 v[42:43], v[42:43], v[154:155] op_sel_hi:[1,0]
	v_pk_mul_f32 v[44:45], v[44:45], v[154:155] op_sel_hi:[1,0]
	v_pk_mul_f32 v[38:39], v[38:39], v[154:155] op_sel_hi:[1,0]
	v_pk_mul_f32 v[40:41], v[40:41], v[154:155] op_sel_hi:[1,0]
	v_pk_mul_f32 v[34:35], v[34:35], v[154:155] op_sel_hi:[1,0]
	v_pk_mul_f32 v[36:37], v[36:37], v[154:155] op_sel_hi:[1,0]
	v_add_f32_e32 v130, v203, v202
	v_add_f32_e32 v131, v204, v205
	v_add_u32_e32 v148, 0xb0, v156
	v_add_f32_e32 v130, v130, v131
	v_mov_b32_e32 v131, v130
	s_nop 1
	v_permlane16_swap_b32 v131, v130
	v_ashrrev_i32_e32 v149, 31, v148
	s_waitcnt lgkmcnt(0)
	v_add_f32_e32 v130, v130, v131
	v_mov_b32_e32 v131, v130
	s_nop 1
	v_permlane32_swap_b32 v131, v130
	s_waitcnt lgkmcnt(0)
	v_add_f32_e32 v130, v130, v131
	v_fmamk_f32 v130, v130, 0x3a800000, v231
	v_rsq_f32_e32 v150, v130
	s_nop 1
	ds_write_b32 v212, v150 offset:640
	s_nop 1
	v_pk_mul_f32 v[30:31], v[30:31], v[150:151] op_sel_hi:[1,0]
	v_pk_mul_f32 v[32:33], v[32:33], v[150:151] op_sel_hi:[1,0]
	v_pk_mul_f32 v[26:27], v[26:27], v[150:151] op_sel_hi:[1,0]
	v_pk_mul_f32 v[28:29], v[28:29], v[150:151] op_sel_hi:[1,0]
	v_pk_mul_f32 v[22:23], v[22:23], v[150:151] op_sel_hi:[1,0]
	v_pk_mul_f32 v[24:25], v[24:25], v[150:151] op_sel_hi:[1,0]
	v_pk_mul_f32 v[18:19], v[18:19], v[150:151] op_sel_hi:[1,0]
	v_pk_mul_f32 v[20:21], v[20:21], v[150:151] op_sel_hi:[1,0]
	v_add_f32_e32 v130, v207, v206
	v_add_f32_e32 v131, v208, v209
	v_mov_b64_e32 v[132:133], s[22:23]
	v_add_f32_e32 v130, v130, v131
	v_mov_b32_e32 v131, v130
	s_nop 1
	v_permlane16_swap_b32 v131, v130
	v_mad_i64_i32 v[180:181], s[30:31], v156, s96, v[132:133]
	s_waitcnt lgkmcnt(0)
	v_add_f32_e32 v130, v130, v131
	v_mov_b32_e32 v131, v130
	s_nop 1
	v_permlane32_swap_b32 v131, v130
	s_waitcnt lgkmcnt(0)
	v_add_f32_e32 v130, v130, v131
	v_lshl_or_b32 v131, s57, 8, v155
	v_ashrrev_i32_e32 v178, 1, v131
	v_mul_f32_e32 v131, 0xbfb8aa3b, v122
	v_exp_f32_e32 v131, v131
	v_ashrrev_i32_e32 v179, 31, v178
	v_lshlrev_b64 v[156:157], 1, v[178:179]
	v_lshl_add_u64 v[178:179], v[180:181], 0, v[156:157]
	v_add_f32_e32 v131, 1.0, v131
	v_rcp_f32_e32 v131, v131
	v_fmamk_f32 v130, v130, 0x3a800000, v231
	v_rsq_f32_e32 v130, v130
	s_nop 1
	ds_write_b32 v212, v130 offset:704
	s_branch .Lmy_rs_join_0
.Lmy_rs_cached_0:
	v_lshlrev_b32_e32 v212, 2, v1
	v_add_u32_e32 v212, 0x21000, v212
	ds_read_b32 v182, v212
	ds_read_b32 v186, v212 offset:64
	ds_read_b32 v190, v212 offset:128
	ds_read_b32 v194, v212 offset:192
	ds_read_b32 v198, v212 offset:512
	ds_read_b32 v202, v212 offset:576
	ds_read_b32 v206, v212 offset:640
	ds_read_b32 v210, v212 offset:704
	s_waitcnt lgkmcnt(0)
	v_lshl_add_u32 v156, s58, 8, v1
	v_ashrrev_i32_e32 v157, 31, v156
	v_lshlrev_b64 v[130:131], 6, v[156:157]
	v_lshl_add_u64 v[130:131], v[142:143], 0, v[130:131]
	v_or_b32_e32 v174, 16, v156
	v_ashrrev_i32_e32 v175, 31, v174
	v_or_b32_e32 v170, 32, v156
	v_ashrrev_i32_e32 v171, 31, v170
	v_or_b32_e32 v166, 48, v156
	v_ashrrev_i32_e32 v167, 31, v166
	v_add_u32_e32 v162, 0x80, v156
	v_ashrrev_i32_e32 v163, 31, v162
	v_add_u32_e32 v158, 0x90, v156
	v_ashrrev_i32_e32 v159, 31, v158
	v_add_u32_e32 v152, 0xa0, v156
	v_ashrrev_i32_e32 v153, 31, v152
	s_and_b64 vcc, exec, s[4:5]
	v_mov_b32_e32 v148, v131
	v_mov_b32_e32 v149, v132
	v_mov_b32_e32 v131, v133
	v_pk_add_f32 v[130:131], v[148:149], v[130:131]
	s_nop 0
	v_add_f32_e32 v130, v130, v131
	v_mov_b32_e32 v131, v130
	s_nop 1
	v_permlane16_swap_b32 v131, v130
	s_waitcnt lgkmcnt(0)
	v_add_f32_e32 v130, v130, v131
	v_mov_b32_e32 v131, v130
	s_nop 1
	v_permlane32_swap_b32 v131, v130
	s_waitcnt lgkmcnt(0)
	v_add_f32_e32 v130, v130, v131
	v_fmamk_f32 v130, v130, 0x3a800000, v231
	v_mov_b32_e32 v176, v182
	s_nop 1
	v_pk_mul_f32 v[122:123], v[122:123], v[176:177] op_sel_hi:[1,0]
	v_pk_mul_f32 v[124:125], v[124:125], v[176:177] op_sel_hi:[1,0]
	v_pk_mul_f32 v[126:127], v[126:127], v[176:177] op_sel_hi:[1,0]
	v_pk_mul_f32 v[128:129], v[128:129], v[176:177] op_sel_hi:[1,0]
	v_pk_mul_f32 v[118:119], v[118:119], v[176:177] op_sel_hi:[1,0]
	v_pk_mul_f32 v[120:121], v[120:121], v[176:177] op_sel_hi:[1,0]
	v_pk_mul_f32 v[114:115], v[114:115], v[176:177] op_sel_hi:[1,0]
	v_pk_mul_f32 v[116:117], v[116:117], v[176:177] op_sel_hi:[1,0]
	v_add_f32_e32 v130, v183, v182
	v_add_f32_e32 v131, v184, v185
	s_nop 0
	v_add_f32_e32 v130, v130, v131
	v_mov_b32_e32 v131, v130
	s_nop 1
	v_permlane16_swap_b32 v131, v130
	s_waitcnt lgkmcnt(0)
; __device__ __forceinline__ float row_rstd16_coop(const float* ssq, int row, int fq, float inv_n) {
;     const f32x4 a = *(const f32x4*)(ssq + (size_t)row * 16 + fq * 4);
;     float s = (a[0] + a[1]) + (a[2] + a[3]);
;     s += __shfl_xor(s, 16); s += __shfl_xor(s, 32);
;     return __builtin_amdgcn_rsqf(s * inv_n + EPS);
; }
;     __device__ __forceinline__ static float sg(float g, float uu) { return g * __builtin_amdgcn_rcpf(1.0f + __builtin_amdgcn_exp2f(-1.4426950408889634f * g)) * uu; }
;     __device__ __forceinline__ void operator()(const f32x4 (&acc)[2][2][4][2], const Unit& u, int wr, int wc, int fr, int fq) const {
;         const int row0 = u.pm * BM + wr * 64 + fr, col0 = u.pn * BM + wc * 32 + 8 * fq;
;         float rsv[2][4];
; #pragma unroll
;         for (int ai = 0; ai < 2; ++ai) {
; #pragma unroll
;             for (int m = 0; m < 4; ++m) rsv[ai][m] = row_rstd16_coop(ssq, row0 + ai * HALF + m * 16, fq, 1.0f / 1024.0f);
;         }
; #pragma unroll
;         for (int ai = 0; ai < 2; ++ai)
; #pragma unroll
;             for (int m = 0; m < 4; ++m) {
;                 const int row = row0 + ai * HALF + m * 16;
;                 const float rs = rsv[ai][m];
;                 bf16_t* rowp = H + (size_t)row * ldh + (col0 >> 1);
; #pragma unroll
;                 for (int bj = 0; bj < 2; ++bj) {
;                     const f32x4 v0 = acc[ai][bj][m][0] * rs, v1 = acc[ai][bj][m][1] * rs;
	v_add_f32_e32 v130, v130, v131
	v_mov_b32_e32 v131, v130
	s_nop 1
	v_permlane32_swap_b32 v131, v130
	s_waitcnt lgkmcnt(0)
	v_add_f32_e32 v130, v130, v131
	v_fmamk_f32 v130, v130, 0x3a800000, v231
	v_mov_b32_e32 v172, v186
	s_nop 1
	v_pk_mul_f32 v[110:111], v[110:111], v[172:173] op_sel_hi:[1,0]
	v_pk_mul_f32 v[112:113], v[112:113], v[172:173] op_sel_hi:[1,0]
	v_pk_mul_f32 v[106:107], v[106:107], v[172:173] op_sel_hi:[1,0]
	v_pk_mul_f32 v[108:109], v[108:109], v[172:173] op_sel_hi:[1,0]
	v_pk_mul_f32 v[102:103], v[102:103], v[172:173] op_sel_hi:[1,0]
	v_pk_mul_f32 v[104:105], v[104:105], v[172:173] op_sel_hi:[1,0]
	v_pk_mul_f32 v[98:99], v[98:99], v[172:173] op_sel_hi:[1,0]
	v_pk_mul_f32 v[100:101], v[100:101], v[172:173] op_sel_hi:[1,0]
	v_add_f32_e32 v130, v187, v186
	v_add_f32_e32 v131, v188, v189
	s_nop 0
	v_add_f32_e32 v130, v130, v131
	v_mov_b32_e32 v131, v130
	s_nop 1
	v_permlane16_swap_b32 v131, v130
	s_waitcnt lgkmcnt(0)
	v_add_f32_e32 v130, v130, v131
	v_mov_b32_e32 v131, v130
	s_nop 1
	v_permlane32_swap_b32 v131, v130
	s_waitcnt lgkmcnt(0)
	v_add_f32_e32 v130, v130, v131
	v_fmamk_f32 v130, v130, 0x3a800000, v231
	v_mov_b32_e32 v168, v190
	s_nop 1
	v_pk_mul_f32 v[94:95], v[94:95], v[168:169] op_sel_hi:[1,0]
	v_pk_mul_f32 v[96:97], v[96:97], v[168:169] op_sel_hi:[1,0]
	v_pk_mul_f32 v[90:91], v[90:91], v[168:169] op_sel_hi:[1,0]
	v_pk_mul_f32 v[92:93], v[92:93], v[168:169] op_sel_hi:[1,0]
	v_pk_mul_f32 v[86:87], v[86:87], v[168:169] op_sel_hi:[1,0]
	v_pk_mul_f32 v[88:89], v[88:89], v[168:169] op_sel_hi:[1,0]
	v_pk_mul_f32 v[82:83], v[82:83], v[168:169] op_sel_hi:[1,0]
	v_pk_mul_f32 v[84:85], v[84:85], v[168:169] op_sel_hi:[1,0]
	v_add_f32_e32 v130, v191, v190
	v_add_f32_e32 v131, v192, v193
	s_nop 0
	v_add_f32_e32 v130, v130, v131
	v_mov_b32_e32 v131, v130
	s_nop 1
	v_permlane16_swap_b32 v131, v130
	s_waitcnt lgkmcnt(0)
	v_add_f32_e32 v130, v130, v131
	v_mov_b32_e32 v131, v130
	s_nop 1
	v_permlane32_swap_b32 v131, v130
	s_waitcnt lgkmcnt(0)
	v_add_f32_e32 v130, v130, v131
	v_fmamk_f32 v130, v130, 0x3a800000, v231
	v_mov_b32_e32 v164, v194
	s_nop 1
	v_pk_mul_f32 v[78:79], v[78:79], v[164:165] op_sel_hi:[1,0]
	v_pk_mul_f32 v[80:81], v[80:81], v[164:165] op_sel_hi:[1,0]
	v_pk_mul_f32 v[74:75], v[74:75], v[164:165] op_sel_hi:[1,0]
	v_pk_mul_f32 v[76:77], v[76:77], v[164:165] op_sel_hi:[1,0]
	v_pk_mul_f32 v[70:71], v[70:71], v[164:165] op_sel_hi:[1,0]
	v_pk_mul_f32 v[72:73], v[72:73], v[164:165] op_sel_hi:[1,0]
	v_pk_mul_f32 v[66:67], v[66:67], v[164:165] op_sel_hi:[1,0]
	v_pk_mul_f32 v[68:69], v[68:69], v[164:165] op_sel_hi:[1,0]
	v_add_f32_e32 v130, v195, v194
	v_add_f32_e32 v131, v196, v197
	s_nop 0
	v_add_f32_e32 v130, v130, v131
	v_mov_b32_e32 v131, v130
	s_nop 1
	v_permlane16_swap_b32 v131, v130
	s_waitcnt lgkmcnt(0)
	v_add_f32_e32 v130, v130, v131
	v_mov_b32_e32 v131, v130
	s_nop 1
	v_permlane32_swap_b32 v131, v130
	s_waitcnt lgkmcnt(0)
	v_add_f32_e32 v130, v130, v131
	v_fmamk_f32 v130, v130, 0x3a800000, v231
	v_mov_b32_e32 v160, v198
	s_nop 1
	v_pk_mul_f32 v[62:63], v[62:63], v[160:161] op_sel_hi:[1,0]
	v_pk_mul_f32 v[64:65], v[64:65], v[160:161] op_sel_hi:[1,0]
	v_pk_mul_f32 v[58:59], v[58:59], v[160:161] op_sel_hi:[1,0]
	v_pk_mul_f32 v[60:61], v[60:61], v[160:161] op_sel_hi:[1,0]
	v_pk_mul_f32 v[54:55], v[54:55], v[160:161] op_sel_hi:[1,0]
	v_pk_mul_f32 v[56:57], v[56:57], v[160:161] op_sel_hi:[1,0]
	v_pk_mul_f32 v[50:51], v[50:51], v[160:161] op_sel_hi:[1,0]
	v_pk_mul_f32 v[52:53], v[52:53], v[160:161] op_sel_hi:[1,0]
	v_add_f32_e32 v130, v199, v198
	v_add_f32_e32 v131, v200, v201
	s_nop 0
	v_add_f32_e32 v130, v130, v131
	v_mov_b32_e32 v131, v130
	s_nop 1
	v_permlane16_swap_b32 v131, v130
	s_waitcnt lgkmcnt(0)
	v_add_f32_e32 v130, v130, v131
	v_mov_b32_e32 v131, v130
	s_nop 1
	v_permlane32_swap_b32 v131, v130
	s_waitcnt lgkmcnt(0)
	v_add_f32_e32 v130, v130, v131
	v_fmamk_f32 v130, v130, 0x3a800000, v231
	v_mov_b32_e32 v154, v202
	s_nop 1
	v_pk_mul_f32 v[46:47], v[46:47], v[154:155] op_sel_hi:[1,0]
	v_pk_mul_f32 v[48:49], v[48:49], v[154:155] op_sel_hi:[1,0]
	v_pk_mul_f32 v[42:43], v[42:43], v[154:155] op_sel_hi:[1,0]
	v_pk_mul_f32 v[44:45], v[44:45], v[154:155] op_sel_hi:[1,0]
	v_pk_mul_f32 v[38:39], v[38:39], v[154:155] op_sel_hi:[1,0]
	v_pk_mul_f32 v[40:41], v[40:41], v[154:155] op_sel_hi:[1,0]
	v_pk_mul_f32 v[34:35], v[34:35], v[154:155] op_sel_hi:[1,0]
	v_pk_mul_f32 v[36:37], v[36:37], v[154:155] op_sel_hi:[1,0]
	v_add_f32_e32 v130, v203, v202
	v_add_f32_e32 v131, v204, v205
	v_add_u32_e32 v148, 0xb0, v156
	v_add_f32_e32 v130, v130, v131
	v_mov_b32_e32 v131, v130
	s_nop 1
	v_permlane16_swap_b32 v131, v130
	v_ashrrev_i32_e32 v149, 31, v148
	s_waitcnt lgkmcnt(0)
	v_add_f32_e32 v130, v130, v131
	v_mov_b32_e32 v131, v130
	s_nop 1
	v_permlane32_swap_b32 v131, v130
	s_waitcnt lgkmcnt(0)
	v_add_f32_e32 v130, v130, v131
	v_fmamk_f32 v130, v130, 0x3a800000, v231
	v_mov_b32_e32 v150, v206
	s_nop 1
	v_pk_mul_f32 v[30:31], v[30:31], v[150:151] op_sel_hi:[1,0]
	v_pk_mul_f32 v[32:33], v[32:33], v[150:151] op_sel_hi:[1,0]
	v_pk_mul_f32 v[26:27], v[26:27], v[150:151] op_sel_hi:[1,0]
	v_pk_mul_f32 v[28:29], v[28:29], v[150:151] op_sel_hi:[1,0]
	v_pk_mul_f32 v[22:23], v[22:23], v[150:151] op_sel_hi:[1,0]
	v_pk_mul_f32 v[24:25], v[24:25], v[150:151] op_sel_hi:[1,0]
	v_pk_mul_f32 v[18:19], v[18:19], v[150:151] op_sel_hi:[1,0]
	v_pk_mul_f32 v[20:21], v[20:21], v[150:151] op_sel_hi:[1,0]
	v_add_f32_e32 v130, v207, v206
	v_add_f32_e32 v131, v208, v209
	v_mov_b64_e32 v[132:133], s[22:23]
	v_add_f32_e32 v130, v130, v131
	v_mov_b32_e32 v131, v130
	s_nop 1
	v_permlane16_swap_b32 v131, v130
	v_mad_i64_i32 v[180:181], s[30:31], v156, s96, v[132:133]
	s_waitcnt lgkmcnt(0)
	v_add_f32_e32 v130, v130, v131
	v_mov_b32_e32 v131, v130
	s_nop 1
	v_permlane32_swap_b32 v131, v130
	s_waitcnt lgkmcnt(0)
	v_add_f32_e32 v130, v130, v131
	v_lshl_or_b32 v131, s57, 8, v155
	v_ashrrev_i32_e32 v178, 1, v131
	v_mul_f32_e32 v131, 0xbfb8aa3b, v122
	v_exp_f32_e32 v131, v131
	v_ashrrev_i32_e32 v179, 31, v178
	v_lshlrev_b64 v[156:157], 1, v[178:179]
	v_lshl_add_u64 v[178:179], v[180:181], 0, v[156:157]
	v_add_f32_e32 v131, 1.0, v131
	v_rcp_f32_e32 v131, v131
	v_fmamk_f32 v130, v130, 0x3a800000, v231
	v_mov_b32_e32 v130, v210
; __device__ __forceinline__ unsigned cvt_pk_bf16(float lo, float hi) { unsigned r; asm volatile("v_cvt_pk_bf16_f32 %0, %1, %2" : "=v"(r) : "v"(lo), "v"(hi)); return r; }
;     __device__ __forceinline__ static float sg(float g, float uu) { return g * __builtin_amdgcn_rcpf(1.0f + __builtin_amdgcn_exp2f(-1.4426950408889634f * g)) * uu; }
;     __device__ __forceinline__ void operator()(const f32x4 (&acc)[2][2][4][2], const Unit& u, int wr, int wc, int fr, int fq) const {
;         const int row0 = u.pm * BM + wr * 64 + fr, col0 = u.pn * BM + wc * 32 + 8 * fq;
;         float rsv[2][4];
; #pragma unroll
;         for (int ai = 0; ai < 2; ++ai) {
; #pragma unroll
;             for (int m = 0; m < 4; ++m) rsv[ai][m] = row_rstd16_coop(ssq, row0 + ai * HALF + m * 16, fq, 1.0f / 1024.0f);
;         }
; #pragma unroll
;         for (int ai = 0; ai < 2; ++ai)
; #pragma unroll
;             for (int m = 0; m < 4; ++m) {
;                 const int row = row0 + ai * HALF + m * 16;
;                 const float rs = rsv[ai][m];
;                 bf16_t* rowp = H + (size_t)row * ldh + (col0 >> 1);
; #pragma unroll
;                 for (int bj = 0; bj < 2; ++bj) {
;                     const f32x4 v0 = acc[ai][bj][m][0] * rs, v1 = acc[ai][bj][m][1] * rs;
;                     u32x2 w; w.x = cvt_pk_bf16(sg(v0[0], v0[1]), sg(v0[2], v0[3])); w.y = cvt_pk_bf16(sg(v1[0], v1[1]), sg(v1[2], v1[3]));
;                     *(u32x2*)(rowp + bj * (HALF / 2)) = w;
;                 }
.Lmy_rs_join_0:
	v_mul_f32_e32 v122, v122, v131
	v_mul_f32_e32 v122, v123, v122
	v_mul_f32_e32 v123, 0xbfb8aa3b, v124
	v_exp_f32_e32 v123, v123
	v_pk_mul_f32 v[14:15], v[14:15], v[130:131] op_sel_hi:[1,0]
	v_pk_mul_f32 v[16:17], v[16:17], v[130:131] op_sel_hi:[1,0]
	v_pk_mul_f32 v[10:11], v[10:11], v[130:131] op_sel_hi:[1,0]
	v_add_f32_e32 v123, 1.0, v123
	v_rcp_f32_e32 v123, v123
	v_pk_mul_f32 v[12:13], v[12:13], v[130:131] op_sel_hi:[1,0]
	v_pk_mul_f32 v[6:7], v[6:7], v[130:131] op_sel_hi:[1,0]
	v_pk_mul_f32 v[8:9], v[8:9], v[130:131] op_sel_hi:[1,0]
	v_mul_f32_e32 v123, v124, v123
	v_mul_f32_e32 v123, v125, v123
	v_cvt_pk_bf16_f32 v122, v122, v123
	v_mul_f32_e32 v123, 0xbfb8aa3b, v126
	v_exp_f32_e32 v123, v123
	v_mul_f32_e32 v124, 0xbfb8aa3b, v128
	v_exp_f32_e32 v124, v124
	v_pk_mul_f32 v[2:3], v[2:3], v[130:131] op_sel_hi:[1,0]
	v_add_f32_e32 v123, 1.0, v123
	v_rcp_f32_e32 v123, v123
	v_add_f32_e32 v124, 1.0, v124
	v_rcp_f32_e32 v124, v124
	v_pk_mul_f32 v[4:5], v[4:5], v[130:131] op_sel_hi:[1,0]
	v_mul_f32_e32 v123, v126, v123
	v_mul_f32_e32 v123, v127, v123
	v_mul_f32_e32 v124, v128, v124
	v_mul_f32_e32 v124, v129, v124
	v_cvt_pk_bf16_f32 v123, v123, v124
	global_store_dwordx2 v[178:179], v[122:123], off
	v_mul_f32_e32 v122, 0xbfb8aa3b, v118
	v_exp_f32_e32 v122, v122
	s_nop 0
	v_add_f32_e32 v122, 1.0, v122
	v_rcp_f32_e32 v122, v122
	s_nop 0
	v_mul_f32_e32 v118, v118, v122
	v_mul_f32_e32 v118, v119, v118
	v_mul_f32_e32 v119, 0xbfb8aa3b, v120
	v_exp_f32_e32 v119, v119
	s_nop 0
	v_add_f32_e32 v119, 1.0, v119
	v_rcp_f32_e32 v119, v119
	s_nop 0
	v_mul_f32_e32 v119, v120, v119
	v_mul_f32_e32 v119, v121, v119
	v_cvt_pk_bf16_f32 v118, v118, v119
	v_mul_f32_e32 v119, 0xbfb8aa3b, v114
	v_exp_f32_e32 v119, v119
	s_nop 0
	v_add_f32_e32 v119, 1.0, v119
	v_rcp_f32_e32 v119, v119
	s_nop 0
	v_mul_f32_e32 v114, v114, v119
	v_mul_f32_e32 v114, v115, v114
	v_mul_f32_e32 v115, 0xbfb8aa3b, v116
	v_exp_f32_e32 v115, v115
	s_nop 0
	v_add_f32_e32 v115, 1.0, v115
	v_rcp_f32_e32 v115, v115
	s_nop 0
	v_mul_f32_e32 v115, v116, v115
	v_mul_f32_e32 v116, 0xbfb8aa3b, v110
	v_exp_f32_e32 v116, v116
	v_mul_f32_e32 v115, v117, v115
	v_cvt_pk_bf16_f32 v119, v114, v115
	global_store_dwordx2 v[178:179], v[118:119], off offset:128
	v_add_f32_e32 v116, 1.0, v116
	v_rcp_f32_e32 v116, v116
	v_mad_i64_i32 v[114:115], s[30:31], v174, s96, v[132:133]
	v_lshl_add_u64 v[114:115], v[114:115], 0, v[156:157]
	v_mul_f32_e32 v110, v110, v116
	v_mul_f32_e32 v110, v111, v110
	v_mul_f32_e32 v111, 0xbfb8aa3b, v112
	v_exp_f32_e32 v111, v111
	s_nop 0
	v_add_f32_e32 v111, 1.0, v111
	v_rcp_f32_e32 v111, v111
	s_nop 0
	v_mul_f32_e32 v111, v112, v111
	v_mul_f32_e32 v111, v113, v111
	v_cvt_pk_bf16_f32 v110, v110, v111
	v_mul_f32_e32 v111, 0xbfb8aa3b, v106
	v_exp_f32_e32 v111, v111
	s_nop 0
	v_add_f32_e32 v111, 1.0, v111
	v_rcp_f32_e32 v111, v111
	s_nop 0
	v_mul_f32_e32 v106, v106, v111
	v_mul_f32_e32 v106, v107, v106
	v_mul_f32_e32 v107, 0xbfb8aa3b, v108
	v_exp_f32_e32 v107, v107
	s_nop 0
	v_add_f32_e32 v107, 1.0, v107
	v_rcp_f32_e32 v107, v107
	s_nop 0
	v_mul_f32_e32 v107, v108, v107
	v_mul_f32_e32 v107, v109, v107
	v_cvt_pk_bf16_f32 v111, v106, v107
	v_mul_f32_e32 v106, 0xbfb8aa3b, v102
	v_exp_f32_e32 v106, v106
	global_store_dwordx2 v[114:115], v[110:111], off
	v_add_f32_e32 v106, 1.0, v106
	v_rcp_f32_e32 v106, v106
	s_nop 0
	v_mul_f32_e32 v102, v102, v106
	v_mul_f32_e32 v102, v103, v102
	v_mul_f32_e32 v103, 0xbfb8aa3b, v104
	v_exp_f32_e32 v103, v103
	s_nop 0
	v_add_f32_e32 v103, 1.0, v103
	v_rcp_f32_e32 v103, v103
	s_nop 0
	v_mul_f32_e32 v103, v104, v103
	v_mul_f32_e32 v103, v105, v103
	v_cvt_pk_bf16_f32 v102, v102, v103
	v_mul_f32_e32 v103, 0xbfb8aa3b, v98
	v_exp_f32_e32 v103, v103
	s_nop 0
	v_add_f32_e32 v103, 1.0, v103
	v_rcp_f32_e32 v103, v103
	s_nop 0
	v_mul_f32_e32 v98, v98, v103
	v_mul_f32_e32 v98, v99, v98
	v_mul_f32_e32 v99, 0xbfb8aa3b, v100
	v_exp_f32_e32 v99, v99
	s_nop 0
	v_add_f32_e32 v99, 1.0, v99
	v_rcp_f32_e32 v99, v99
	s_nop 0
	v_mul_f32_e32 v99, v100, v99
	v_mul_f32_e32 v100, 0xbfb8aa3b, v94
	v_exp_f32_e32 v100, v100
	v_mul_f32_e32 v99, v101, v99
	v_cvt_pk_bf16_f32 v103, v98, v99
	global_store_dwordx2 v[114:115], v[102:103], off offset:128
	v_add_f32_e32 v100, 1.0, v100
	v_rcp_f32_e32 v100, v100
	v_mad_i64_i32 v[98:99], s[30:31], v170, s96, v[132:133]
	v_lshl_add_u64 v[98:99], v[98:99], 0, v[156:157]
	v_mul_f32_e32 v94, v94, v100
	v_mul_f32_e32 v94, v95, v94
	v_mul_f32_e32 v95, 0xbfb8aa3b, v96
	v_exp_f32_e32 v95, v95
	s_nop 0
	v_add_f32_e32 v95, 1.0, v95
	v_rcp_f32_e32 v95, v95
	s_nop 0
	v_mul_f32_e32 v95, v96, v95
	v_mul_f32_e32 v95, v97, v95
	v_cvt_pk_bf16_f32 v94, v94, v95
	v_mul_f32_e32 v95, 0xbfb8aa3b, v90
	v_exp_f32_e32 v95, v95
	s_nop 0
	v_add_f32_e32 v95, 1.0, v95
	v_rcp_f32_e32 v95, v95
	s_nop 0
	v_mul_f32_e32 v90, v90, v95
	v_mul_f32_e32 v90, v91, v90
	v_mul_f32_e32 v91, 0xbfb8aa3b, v92
	v_exp_f32_e32 v91, v91
	s_nop 0
	v_add_f32_e32 v91, 1.0, v91
	v_rcp_f32_e32 v91, v91
	s_nop 0
	v_mul_f32_e32 v91, v92, v91
	v_mul_f32_e32 v91, v93, v91
	v_cvt_pk_bf16_f32 v95, v90, v91
	v_mul_f32_e32 v90, 0xbfb8aa3b, v86
	v_exp_f32_e32 v90, v90
	global_store_dwordx2 v[98:99], v[94:95], off
	v_add_f32_e32 v90, 1.0, v90
	v_rcp_f32_e32 v90, v90
	s_nop 0
	v_mul_f32_e32 v86, v86, v90
	v_mul_f32_e32 v86, v87, v86
	v_mul_f32_e32 v87, 0xbfb8aa3b, v88
	v_exp_f32_e32 v87, v87
	s_nop 0
	v_add_f32_e32 v87, 1.0, v87
	v_rcp_f32_e32 v87, v87
	s_nop 0
	v_mul_f32_e32 v87, v88, v87
	v_mul_f32_e32 v87, v89, v87
	v_cvt_pk_bf16_f32 v86, v86, v87
	v_mul_f32_e32 v87, 0xbfb8aa3b, v82
	v_exp_f32_e32 v87, v87
	s_nop 0
	v_add_f32_e32 v87, 1.0, v87
	v_rcp_f32_e32 v87, v87
	s_nop 0
	v_mul_f32_e32 v82, v82, v87
; __device__ __forceinline__ unsigned cvt_pk_bf16(float lo, float hi) { unsigned r; asm volatile("v_cvt_pk_bf16_f32 %0, %1, %2" : "=v"(r) : "v"(lo), "v"(hi)); return r; }
;     __device__ __forceinline__ static float sg(float g, float uu) { return g * __builtin_amdgcn_rcpf(1.0f + __builtin_amdgcn_exp2f(-1.4426950408889634f * g)) * uu; }
;     __device__ __forceinline__ void operator()(const f32x4 (&acc)[2][2][4][2], const Unit& u, int wr, int wc, int fr, int fq) const {
;         const int row0 = u.pm * BM + wr * 64 + fr, col0 = u.pn * BM + wc * 32 + 8 * fq;
;         float rsv[2][4];
; #pragma unroll
;         for (int ai = 0; ai < 2; ++ai) {
; #pragma unroll
;             for (int m = 0; m < 4; ++m) rsv[ai][m] = row_rstd16_coop(ssq, row0 + ai * HALF + m * 16, fq, 1.0f / 1024.0f);
;         }
; #pragma unroll
;         for (int ai = 0; ai < 2; ++ai)
; #pragma unroll
;             for (int m = 0; m < 4; ++m) {
;                 const int row = row0 + ai * HALF + m * 16;
;                 const float rs = rsv[ai][m];
;                 bf16_t* rowp = H + (size_t)row * ldh + (col0 >> 1);
; #pragma unroll
;                 for (int bj = 0; bj < 2; ++bj) {
;                     const f32x4 v0 = acc[ai][bj][m][0] * rs, v1 = acc[ai][bj][m][1] * rs;
;                     u32x2 w; w.x = cvt_pk_bf16(sg(v0[0], v0[1]), sg(v0[2], v0[3])); w.y = cvt_pk_bf16(sg(v1[0], v1[1]), sg(v1[2], v1[3]));
;                     *(u32x2*)(rowp + bj * (HALF / 2)) = w;
;                 }
	v_mul_f32_e32 v82, v83, v82
	v_mul_f32_e32 v83, 0xbfb8aa3b, v84
	v_exp_f32_e32 v83, v83
	s_nop 0
	v_add_f32_e32 v83, 1.0, v83
	v_rcp_f32_e32 v83, v83
	s_nop 0
	v_mul_f32_e32 v83, v84, v83
	v_mul_f32_e32 v84, 0xbfb8aa3b, v78
	v_exp_f32_e32 v84, v84
	v_mul_f32_e32 v83, v85, v83
	v_cvt_pk_bf16_f32 v87, v82, v83
	global_store_dwordx2 v[98:99], v[86:87], off offset:128
	v_add_f32_e32 v84, 1.0, v84
	v_rcp_f32_e32 v84, v84
	v_mad_i64_i32 v[82:83], s[30:31], v166, s96, v[132:133]
	v_lshl_add_u64 v[82:83], v[82:83], 0, v[156:157]
	v_mul_f32_e32 v78, v78, v84
	v_mul_f32_e32 v78, v79, v78
	v_mul_f32_e32 v79, 0xbfb8aa3b, v80
	v_exp_f32_e32 v79, v79
	s_nop 0
	v_add_f32_e32 v79, 1.0, v79
	v_rcp_f32_e32 v79, v79
	s_nop 0
	v_mul_f32_e32 v79, v80, v79
	v_mul_f32_e32 v79, v81, v79
	v_cvt_pk_bf16_f32 v78, v78, v79
	v_mul_f32_e32 v79, 0xbfb8aa3b, v74
	v_exp_f32_e32 v79, v79
	s_nop 0
	v_add_f32_e32 v79, 1.0, v79
	v_rcp_f32_e32 v79, v79
	s_nop 0
	v_mul_f32_e32 v74, v74, v79
	v_mul_f32_e32 v74, v75, v74
	v_mul_f32_e32 v75, 0xbfb8aa3b, v76
	v_exp_f32_e32 v75, v75
	s_nop 0
	v_add_f32_e32 v75, 1.0, v75
	v_rcp_f32_e32 v75, v75
	s_nop 0
	v_mul_f32_e32 v75, v76, v75
	v_mul_f32_e32 v75, v77, v75
	v_cvt_pk_bf16_f32 v79, v74, v75
	v_mul_f32_e32 v74, 0xbfb8aa3b, v70
	v_exp_f32_e32 v74, v74
	global_store_dwordx2 v[82:83], v[78:79], off
	v_add_f32_e32 v74, 1.0, v74
	v_rcp_f32_e32 v74, v74
	s_nop 0
	v_mul_f32_e32 v70, v70, v74
	v_mul_f32_e32 v70, v71, v70
	v_mul_f32_e32 v71, 0xbfb8aa3b, v72
	v_exp_f32_e32 v71, v71
	s_nop 0
	v_add_f32_e32 v71, 1.0, v71
	v_rcp_f32_e32 v71, v71
	s_nop 0
	v_mul_f32_e32 v71, v72, v71
	v_mul_f32_e32 v71, v73, v71
	v_cvt_pk_bf16_f32 v70, v70, v71
	v_mul_f32_e32 v71, 0xbfb8aa3b, v66
	v_exp_f32_e32 v71, v71
	s_nop 0
	v_add_f32_e32 v71, 1.0, v71
	v_rcp_f32_e32 v71, v71
	s_nop 0
	v_mul_f32_e32 v66, v66, v71
	v_mul_f32_e32 v66, v67, v66
	v_mul_f32_e32 v67, 0xbfb8aa3b, v68
	v_exp_f32_e32 v67, v67
	s_nop 0
	v_add_f32_e32 v67, 1.0, v67
	v_rcp_f32_e32 v67, v67
	s_nop 0
	v_mul_f32_e32 v67, v68, v67
	v_mul_f32_e32 v68, 0xbfb8aa3b, v62
	v_exp_f32_e32 v68, v68
	v_mul_f32_e32 v67, v69, v67
	v_cvt_pk_bf16_f32 v71, v66, v67
	global_store_dwordx2 v[82:83], v[70:71], off offset:128
	v_add_f32_e32 v68, 1.0, v68
	v_rcp_f32_e32 v68, v68
	v_mad_i64_i32 v[66:67], s[30:31], v162, s96, v[132:133]
	v_lshl_add_u64 v[66:67], v[66:67], 0, v[156:157]
	v_mul_f32_e32 v62, v62, v68
	v_mul_f32_e32 v62, v63, v62
	v_mul_f32_e32 v63, 0xbfb8aa3b, v64
	v_exp_f32_e32 v63, v63
	s_nop 0
	v_add_f32_e32 v63, 1.0, v63
	v_rcp_f32_e32 v63, v63
	s_nop 0
	v_mul_f32_e32 v63, v64, v63
	v_mul_f32_e32 v63, v65, v63
	v_cvt_pk_bf16_f32 v62, v62, v63
	v_mul_f32_e32 v63, 0xbfb8aa3b, v58
	v_exp_f32_e32 v63, v63
	s_nop 0
	v_add_f32_e32 v63, 1.0, v63
	v_rcp_f32_e32 v63, v63
	s_nop 0
	v_mul_f32_e32 v58, v58, v63
	v_mul_f32_e32 v58, v59, v58
	v_mul_f32_e32 v59, 0xbfb8aa3b, v60
	v_exp_f32_e32 v59, v59
	s_nop 0
	v_add_f32_e32 v59, 1.0, v59
	v_rcp_f32_e32 v59, v59
	s_nop 0
	v_mul_f32_e32 v59, v60, v59
	v_mul_f32_e32 v59, v61, v59
	v_cvt_pk_bf16_f32 v63, v58, v59
	v_mul_f32_e32 v58, 0xbfb8aa3b, v54
	v_exp_f32_e32 v58, v58
	global_store_dwordx2 v[66:67], v[62:63], off
	v_add_f32_e32 v58, 1.0, v58
	v_rcp_f32_e32 v58, v58
	s_nop 0
	v_mul_f32_e32 v54, v54, v58
	v_mul_f32_e32 v54, v55, v54
	v_mul_f32_e32 v55, 0xbfb8aa3b, v56
	v_exp_f32_e32 v55, v55
	s_nop 0
	v_add_f32_e32 v55, 1.0, v55
	v_rcp_f32_e32 v55, v55
	s_nop 0
	v_mul_f32_e32 v55, v56, v55
	v_mul_f32_e32 v55, v57, v55
	v_cvt_pk_bf16_f32 v54, v54, v55
	v_mul_f32_e32 v55, 0xbfb8aa3b, v50
	v_exp_f32_e32 v55, v55
	s_nop 0
	v_add_f32_e32 v55, 1.0, v55
	v_rcp_f32_e32 v55, v55
	s_nop 0
	v_mul_f32_e32 v50, v50, v55
	v_mul_f32_e32 v50, v51, v50
	v_mul_f32_e32 v51, 0xbfb8aa3b, v52
	v_exp_f32_e32 v51, v51
	s_nop 0
	v_add_f32_e32 v51, 1.0, v51
	v_rcp_f32_e32 v51, v51
	s_nop 0
	v_mul_f32_e32 v51, v52, v51
	v_mul_f32_e32 v52, 0xbfb8aa3b, v46
	v_exp_f32_e32 v52, v52
	v_mul_f32_e32 v51, v53, v51
	v_cvt_pk_bf16_f32 v55, v50, v51
	global_store_dwordx2 v[66:67], v[54:55], off offset:128
	v_add_f32_e32 v52, 1.0, v52
	v_rcp_f32_e32 v52, v52
	v_mad_i64_i32 v[50:51], s[30:31], v158, s96, v[132:133]
	v_lshl_add_u64 v[50:51], v[50:51], 0, v[156:157]
	v_mul_f32_e32 v46, v46, v52
	v_mul_f32_e32 v46, v47, v46
	v_mul_f32_e32 v47, 0xbfb8aa3b, v48
	v_exp_f32_e32 v47, v47
	s_nop 0
	v_add_f32_e32 v47, 1.0, v47
	v_rcp_f32_e32 v47, v47
	s_nop 0
	v_mul_f32_e32 v47, v48, v47
	v_mul_f32_e32 v47, v49, v47
	v_cvt_pk_bf16_f32 v46, v46, v47
	v_mul_f32_e32 v47, 0xbfb8aa3b, v42
	v_exp_f32_e32 v47, v47
	s_nop 0
	v_add_f32_e32 v47, 1.0, v47
	v_rcp_f32_e32 v47, v47
	s_nop 0
	v_mul_f32_e32 v42, v42, v47
	v_mul_f32_e32 v42, v43, v42
	v_mul_f32_e32 v43, 0xbfb8aa3b, v44
	v_exp_f32_e32 v43, v43
	s_nop 0
	v_add_f32_e32 v43, 1.0, v43
; __device__ __forceinline__ unsigned cvt_pk_bf16(float lo, float hi) { unsigned r; asm volatile("v_cvt_pk_bf16_f32 %0, %1, %2" : "=v"(r) : "v"(lo), "v"(hi)); return r; }
; #define PG8_BAR __builtin_amdgcn_s_barrier()
; template <class Epi, class Sched, bool ALIGN_EPI = false, bool SP2 = false>
; __device__ __forceinline__ void gemm_phase(PG8_LAS unsigned char* lds, const Gemm g, const Sched& S, const Epi& E) {
;     ...
;         if constexpr (ALIGN_EPI) { if (wr == 0) PG8_BAR; }
;         if constexpr (!Epi::AFTER_DRAIN) { E(acc, cur, wr, wc, fr, fq); S.done(cur); }
;         if (!has_next) break;
; #pragma unroll
;         for (int a = 0; a < 2; ++a)
; #pragma unroll
;             for (int b = 0; b < 2; ++b)
; #pragma unroll
;                 for (int m = 0; m < 4; ++m)
; #pragma unroll
;                     for (int n = 0; n < 2; ++n) acc[a][b][m][n] = (f32x4){0.f, 0.f, 0.f, 0.f};
;         cur = nxt; cA = nA; cB = nB; ++ui;
;         if constexpr (ALIGN_EPI) { if (wr == 1) PG8_BAR; }
;     __device__ __forceinline__ static float sg(float g, float uu) { return g * __builtin_amdgcn_rcpf(1.0f + __builtin_amdgcn_exp2f(-1.4426950408889634f * g)) * uu; }
;     __device__ __forceinline__ void operator()(const f32x4 (&acc)[2][2][4][2], const Unit& u, int wr, int wc, int fr, int fq) const {
;         const int row0 = u.pm * BM + wr * 64 + fr, col0 = u.pn * BM + wc * 32 + 8 * fq;
;         float rsv[2][4];
; #pragma unroll
;         for (int ai = 0; ai < 2; ++ai) {
; #pragma unroll
;             for (int m = 0; m < 4; ++m) rsv[ai][m] = row_rstd16_coop(ssq, row0 + ai * HALF + m * 16, fq, 1.0f / 1024.0f);
;         }
; #pragma unroll
;         for (int ai = 0; ai < 2; ++ai)
; #pragma unroll
;             for (int m = 0; m < 4; ++m) {
;                 const int row = row0 + ai * HALF + m * 16;
;                 const float rs = rsv[ai][m];
;                 bf16_t* rowp = H + (size_t)row * ldh + (col0 >> 1);
; #pragma unroll
;                 for (int bj = 0; bj < 2; ++bj) {
;                     const f32x4 v0 = acc[ai][bj][m][0] * rs, v1 = acc[ai][bj][m][1] * rs;
;                     u32x2 w; w.x = cvt_pk_bf16(sg(v0[0], v0[1]), sg(v0[2], v0[3])); w.y = cvt_pk_bf16(sg(v1[0], v1[1]), sg(v1[2], v1[3]));
;                     *(u32x2*)(rowp + bj * (HALF / 2)) = w;
;                 }
	v_rcp_f32_e32 v43, v43
	s_nop 0
	v_mul_f32_e32 v43, v44, v43
	v_mul_f32_e32 v43, v45, v43
	v_cvt_pk_bf16_f32 v47, v42, v43
	v_mul_f32_e32 v42, 0xbfb8aa3b, v38
	v_exp_f32_e32 v42, v42
	global_store_dwordx2 v[50:51], v[46:47], off
	v_add_f32_e32 v42, 1.0, v42
	v_rcp_f32_e32 v42, v42
	s_nop 0
	v_mul_f32_e32 v38, v38, v42
	v_mul_f32_e32 v38, v39, v38
	v_mul_f32_e32 v39, 0xbfb8aa3b, v40
	v_exp_f32_e32 v39, v39
	s_nop 0
	v_add_f32_e32 v39, 1.0, v39
	v_rcp_f32_e32 v39, v39
	s_nop 0
	v_mul_f32_e32 v39, v40, v39
	v_mul_f32_e32 v39, v41, v39
	v_cvt_pk_bf16_f32 v38, v38, v39
	v_mul_f32_e32 v39, 0xbfb8aa3b, v34
	v_exp_f32_e32 v39, v39
	s_nop 0
	v_add_f32_e32 v39, 1.0, v39
	v_rcp_f32_e32 v39, v39
	s_nop 0
	v_mul_f32_e32 v34, v34, v39
	v_mul_f32_e32 v34, v35, v34
	v_mul_f32_e32 v35, 0xbfb8aa3b, v36
	v_exp_f32_e32 v35, v35
	s_nop 0
	v_add_f32_e32 v35, 1.0, v35
	v_rcp_f32_e32 v35, v35
	s_nop 0
	v_mul_f32_e32 v35, v36, v35
	v_mul_f32_e32 v36, 0xbfb8aa3b, v30
	v_exp_f32_e32 v36, v36
	v_mul_f32_e32 v35, v37, v35
	v_cvt_pk_bf16_f32 v39, v34, v35
	global_store_dwordx2 v[50:51], v[38:39], off offset:128
	v_add_f32_e32 v36, 1.0, v36
	v_rcp_f32_e32 v36, v36
	v_mad_i64_i32 v[34:35], s[30:31], v152, s96, v[132:133]
	v_lshl_add_u64 v[34:35], v[34:35], 0, v[156:157]
	v_mul_f32_e32 v30, v30, v36
	v_mul_f32_e32 v30, v31, v30
	v_mul_f32_e32 v31, 0xbfb8aa3b, v32
	v_exp_f32_e32 v31, v31
	s_nop 0
	v_add_f32_e32 v31, 1.0, v31
	v_rcp_f32_e32 v31, v31
	s_nop 0
	v_mul_f32_e32 v31, v32, v31
	v_mul_f32_e32 v31, v33, v31
	v_cvt_pk_bf16_f32 v30, v30, v31
	v_mul_f32_e32 v31, 0xbfb8aa3b, v26
	v_exp_f32_e32 v31, v31
	s_nop 0
	v_add_f32_e32 v31, 1.0, v31
	v_rcp_f32_e32 v31, v31
	s_nop 0
	v_mul_f32_e32 v26, v26, v31
	v_mul_f32_e32 v26, v27, v26
	v_mul_f32_e32 v27, 0xbfb8aa3b, v28
	v_exp_f32_e32 v27, v27
	s_nop 0
	v_add_f32_e32 v27, 1.0, v27
	v_rcp_f32_e32 v27, v27
	s_nop 0
	v_mul_f32_e32 v27, v28, v27
	v_mul_f32_e32 v27, v29, v27
	v_cvt_pk_bf16_f32 v31, v26, v27
	v_mul_f32_e32 v26, 0xbfb8aa3b, v22
	v_exp_f32_e32 v26, v26
	global_store_dwordx2 v[34:35], v[30:31], off
	v_add_f32_e32 v26, 1.0, v26
	v_rcp_f32_e32 v26, v26
	s_nop 0
	v_mul_f32_e32 v22, v22, v26
	v_mul_f32_e32 v22, v23, v22
	v_mul_f32_e32 v23, 0xbfb8aa3b, v24
	v_exp_f32_e32 v23, v23
	s_nop 0
	v_add_f32_e32 v23, 1.0, v23
	v_rcp_f32_e32 v23, v23
	s_nop 0
	v_mul_f32_e32 v23, v24, v23
	v_mul_f32_e32 v23, v25, v23
	v_cvt_pk_bf16_f32 v22, v22, v23
	v_mul_f32_e32 v23, 0xbfb8aa3b, v18
	v_exp_f32_e32 v23, v23
	s_nop 0
	v_add_f32_e32 v23, 1.0, v23
	v_rcp_f32_e32 v23, v23
	s_nop 0
	v_mul_f32_e32 v18, v18, v23
	v_mul_f32_e32 v18, v19, v18
	v_mul_f32_e32 v19, 0xbfb8aa3b, v20
	v_exp_f32_e32 v19, v19
	s_nop 0
	v_add_f32_e32 v19, 1.0, v19
	v_rcp_f32_e32 v19, v19
	s_nop 0
	v_mul_f32_e32 v19, v20, v19
	v_mul_f32_e32 v20, 0xbfb8aa3b, v14
	v_exp_f32_e32 v20, v20
	v_mul_f32_e32 v19, v21, v19
	v_cvt_pk_bf16_f32 v23, v18, v19
	global_store_dwordx2 v[34:35], v[22:23], off offset:128
	v_add_f32_e32 v20, 1.0, v20
	v_rcp_f32_e32 v20, v20
	v_mad_i64_i32 v[18:19], s[30:31], v148, s96, v[132:133]
	v_lshl_add_u64 v[18:19], v[18:19], 0, v[156:157]
	v_mul_f32_e32 v14, v14, v20
	v_mul_f32_e32 v14, v15, v14
	v_mul_f32_e32 v15, 0xbfb8aa3b, v16
	v_exp_f32_e32 v15, v15
	s_mov_b64 s[30:31], -1
	v_add_f32_e32 v15, 1.0, v15
	v_rcp_f32_e32 v15, v15
	s_nop 0
	v_mul_f32_e32 v15, v16, v15
	v_mul_f32_e32 v15, v17, v15
	v_cvt_pk_bf16_f32 v14, v14, v15
	v_mul_f32_e32 v15, 0xbfb8aa3b, v10
	v_exp_f32_e32 v15, v15
	s_nop 0
	v_add_f32_e32 v15, 1.0, v15
	v_rcp_f32_e32 v15, v15
	s_nop 0
	v_mul_f32_e32 v10, v10, v15
	v_mul_f32_e32 v10, v11, v10
	v_mul_f32_e32 v11, 0xbfb8aa3b, v12
	v_exp_f32_e32 v11, v11
	s_nop 0
	v_add_f32_e32 v11, 1.0, v11
	v_rcp_f32_e32 v11, v11
	s_nop 0
	v_mul_f32_e32 v11, v12, v11
	v_mul_f32_e32 v11, v13, v11
	v_cvt_pk_bf16_f32 v15, v10, v11
	v_mul_f32_e32 v10, 0xbfb8aa3b, v6
	v_exp_f32_e32 v10, v10
	global_store_dwordx2 v[18:19], v[14:15], off
	v_add_f32_e32 v10, 1.0, v10
	v_rcp_f32_e32 v10, v10
	s_nop 0
	v_mul_f32_e32 v6, v6, v10
	v_mul_f32_e32 v6, v7, v6
	v_mul_f32_e32 v7, 0xbfb8aa3b, v8
	v_exp_f32_e32 v7, v7
	s_nop 0
	v_add_f32_e32 v7, 1.0, v7
	v_rcp_f32_e32 v7, v7
	s_nop 0
	v_mul_f32_e32 v7, v8, v7
	v_mul_f32_e32 v7, v9, v7
	v_cvt_pk_bf16_f32 v6, v6, v7
	v_mul_f32_e32 v7, 0xbfb8aa3b, v2
	v_exp_f32_e32 v7, v7
	s_nop 0
	v_add_f32_e32 v7, 1.0, v7
	v_rcp_f32_e32 v7, v7
	s_nop 0
	v_mul_f32_e32 v2, v2, v7
	v_mul_f32_e32 v2, v3, v2
	v_mul_f32_e32 v3, 0xbfb8aa3b, v4
	v_exp_f32_e32 v3, v3
	s_nop 0
	v_add_f32_e32 v3, 1.0, v3
	v_rcp_f32_e32 v3, v3
	s_nop 0
	v_mul_f32_e32 v3, v4, v3
	v_mul_f32_e32 v3, v5, v3
	v_cvt_pk_bf16_f32 v7, v2, v3
	global_store_dwordx2 v[18:19], v[6:7], off offset:128
	s_cbranch_vccnz .LBB0_3152
	s_andn2_b64 vcc, exec, s[20:21]
	s_cbranch_vccnz .LBB0_3151
	s_barrier
	s_branch .LBB0_3151

; #define PG8_STAGE(bufoff, gbase, voff) do { _Pragma("unroll") for (int _i = 0; _i < 2; ++_i) \
;         __builtin_amdgcn_global_load_lds((const unsigned*)((const char*)(gbase) + (voff)[_i]), (PG8_LAS unsigned*)(lds + (bufoff) + ldsw + _i * 8192), 16, 0, 0); } while (0)
; #define PG8_WAIT_V(n) asm volatile("s_waitcnt vmcnt(" #n ")" ::: "memory")
; #define PG8_BAR __builtin_amdgcn_s_barrier()
; template <class Epi, class Sched, bool ALIGN_EPI = false, bool SP2 = false>
; __device__ __forceinline__ void gemm_phase(PG8_LAS unsigned char* lds, const Gemm g, const Sched& S, const Epi& E) {
;     ...
;     const int tid = tid_, wid = __builtin_amdgcn_readfirstlane(tid >> 6), lane = tid & 63, wr = wid >> 2, wc = wid & 3, fr = lane & 15, fq = lane >> 4;
;     const int K = g.K, nt = K / BK;
;     unsigned voffA[2], voffB[2];
; #pragma unroll
;     for (int i = 0; i < 2; ++i) { int R, C; stage_rc(tid * 16 + i * 8192, R, C); const int Rb = Epi::PERM ? ((R & ~31) + perm32(R & 31)) : R;
;         voffA[i] = (unsigned)(R * K + C) * 2u; voffB[i] = (unsigned)(Rb * K + C) * 2u; }
;     const size_t kstep = (size_t)(BK * 2);
;     const size_t hstep = (size_t)HALF * K * 2;
;     const size_t tstep = 2 * hstep;
;     const unsigned ldsw = (unsigned)wid * 1024u;
;     const int aoff = lds_byte(wr * 64 + fr, fq * 8), boff = lds_byte(wc * 32 + fr, fq * 8);
;     ...
;         PG8_STAGE(PG8_SB(0, 0), cB, voffB); PG8_STAGE(PG8_SB(0, 1), cB + hstep, voffB); PG8_STAGE(PG8_SA(0, 0), cA, voffA); PG8_STAGE(PG8_SA(0, 1), cA + hstep, voffA);
;         if (wr == 1) PG8_BAR;
;         PG8_WAIT_V(2); PG8_BAR;
;         PG8_STAGE(PG8_SB(1, 0), cB + kstep, voffB); PG8_STAGE(PG8_SA(1, 0), cA + kstep, voffA); PG8_STAGE(PG8_SB(1, 1), cB + hstep + kstep, voffB);
;         PG8_WAIT_V(6); PG8_BAR;
.LBB0_3331:
	s_add_u32 s18, s0, 0x8c00000
	s_addc_u32 s19, s1, 0
	s_add_i32 m0, s43, 0x18000
	v_lshl_add_u64 v[2:3], v[2:3], 0, s[92:93]
	s_waitcnt vmcnt(2)
	s_barrier
	global_load_lds_dwordx4 v[2:3], off
	v_lshl_add_u64 v[2:3], v[4:5], 0, s[92:93]
	s_add_i32 m0, s43, 0x1a000
	s_add_i32 s47, s43, 0x8000
	global_load_lds_dwordx4 v[2:3], off
	v_lshl_add_u64 v[2:3], v[10:11], 0, s[92:93]
	s_mov_b32 m0, s47
	s_add_i32 s48, s43, 0xa000
	global_load_lds_dwordx4 v[2:3], off
	v_lshl_add_u64 v[2:3], v[12:13], 0, s[92:93]
	s_mov_b32 m0, s48
	v_bfe_u32 v4, v14, 4, 2
	global_load_lds_dwordx4 v[2:3], off
	s_add_i32 m0, s43, 0x1c000
	v_lshl_add_u64 v[2:3], v[6:7], 0, s[92:93]
	global_load_lds_dwordx4 v[2:3], off
	v_lshl_add_u64 v[2:3], v[8:9], 0, s[92:93]
	s_add_i32 m0, s43, 0x1e000
	s_lshr_b32 s5, s5, 26
	global_load_lds_dwordx4 v[2:3], off
	v_and_b32_e32 v3, 15, v14
	s_add_i32 s5, s4, s5
	v_lshlrev_b32_e32 v2, 4, v4
	v_lshlrev_b32_e32 v5, 2, v14
	s_ashr_i32 s49, s5, 6
	v_lshl_or_b32 v1, s20, 6, v3
	v_lshl_or_b32 v3, v3, 6, v2
	s_lshl_b32 s5, s20, 13
	v_and_b32_e32 v5, 32, v5
	v_bitop3_b32 v6, v3, s5, v5 bitop3:0xde
	s_lshl_b32 s5, s21, 5
	s_and_b32 s5, s5, 0x60
	s_lshl_b32 s20, s5, 7
	s_waitcnt vmcnt(0)
	v_bitop3_b32 v149, v3, s20, v5 bitop3:0xde
	v_mov_b32_e32 v3, v0
	v_lshl_add_u64 v[2:3], s[0:1], 0, v[2:3]
	s_mov_b64 s[0:1], 0x8000000
	v_lshl_add_u64 v[142:143], v[2:3], 0, s[0:1]
	v_add_u32_e32 v2, v20, v18
	s_cmp_gt_i32 s4, 63
	v_add_lshl_u32 v2, v2, v19, 1
	v_mov_b32_e32 v3, v0
	s_waitcnt vmcnt(6)
	s_cselect_b64 s[20:21], -1, 0
	s_add_i32 s50, s49, -2
	v_lshl_add_u64 v[144:145], s[12:13], 0, v[2:3]
	v_add_u32_e32 v2, v17, v15
	s_cmpk_lt_u32 s22, 0x100
	v_add_lshl_u32 v2, v2, v16, 1
	s_cselect_b64 s[22:23], -1, 0
	v_lshl_or_b32 v151, v4, 3, s5
	v_lshl_add_u64 v[146:147], s[12:13], 0, v[2:3]
	s_mov_b32 s51, 0
	v_add_u32_e32 v153, 0, v6
	s_barrier
	s_mov_b32 s32, -1
	s_branch .LBB0_3334

; __device__ __forceinline__ unsigned cvt_pk_bf16(float lo, float hi) { unsigned r; asm volatile("v_cvt_pk_bf16_f32 %0, %1, %2" : "=v"(r) : "v"(lo), "v"(hi)); return r; }
; __device__ __forceinline__ float row_rstd16_coop(const float* ssq, int row, int fq, float inv_n) {
;     const f32x4 a = *(const f32x4*)(ssq + (size_t)row * 16 + fq * 4);
;     float s = (a[0] + a[1]) + (a[2] + a[3]);
;     s += __shfl_xor(s, 16); s += __shfl_xor(s, 32);
;     return __builtin_amdgcn_rsqf(s * inv_n + EPS);
; }
;     __device__ __forceinline__ void operator()(const f32x4 (&acc)[2][2][4][2], const Unit& u, int wr, int wc, int fr, int fq) const {
;     ...
;         for (int ai = 0; ai < 2; ++ai)
; #pragma unroll
;             for (int m = 0; m < 4; ++m) {
;                 const int row = row0 + ai * HALF + m * 16;
;                 const float rs = rsv[ai][m];
;                 bf16_t* rowp = O + (size_t)row * ldc + col0;
; #pragma unroll
;                 for (int bj = 0; bj < 2; ++bj) {
;                     const f32x4 v0 = acc[ai][bj][m][0] * rs, v1 = acc[ai][bj][m][1] * rs;
;                     u32x4 w; w.x = cvt_pk_bf16(v0[0], v0[1]); w.y = cvt_pk_bf16(v0[2], v0[3]); w.z = cvt_pk_bf16(v1[0], v1[1]); w.w = cvt_pk_bf16(v1[2], v1[3]);
;                     *(u32x4*)(rowp + bj * HALF) = w;
;                 }
.LBB0_3349:
	s_cmp_eq_u32 s55, s32
	s_cbranch_scc1 .Lmy_rs_cached_1
	s_mov_b32 s32, s55
	v_lshlrev_b32_e32 v210, 2, v1
	v_add_u32_e32 v210, 0x21000, v210
	v_lshl_add_u32 v162, s55, 8, v1
	v_ashrrev_i32_e32 v163, 31, v162
	v_lshlrev_b64 v[130:131], 6, v[162:163]
	v_lshl_add_u64 v[130:131], v[142:143], 0, v[130:131]
	global_load_dwordx4 v[180:183], v[130:131], off offset:1024
	global_load_dwordx4 v[184:187], v[130:131], off offset:2048
	global_load_dwordx4 v[188:191], v[130:131], off offset:3072
	v_add_co_u32_e32 v208, vcc, 0x2000, v130
	s_nop 1
	v_addc_co_u32_e32 v209, vcc, 0, v131, vcc
	global_load_dwordx4 v[192:195], v[208:209], off
	global_load_dwordx4 v[196:199], v[208:209], off offset:1024
	global_load_dwordx4 v[200:203], v[208:209], off offset:2048
	global_load_dwordx4 v[204:207], v[208:209], off offset:3072
	global_load_dwordx4 v[130:133], v[130:131], off
	v_or_b32_e32 v164, 16, v162
	v_ashrrev_i32_e32 v165, 31, v164
	v_or_b32_e32 v166, 32, v162
	v_ashrrev_i32_e32 v167, 31, v166
	v_or_b32_e32 v168, 48, v162
	v_ashrrev_i32_e32 v169, 31, v168
	v_add_u32_e32 v170, 0x80, v162
	v_ashrrev_i32_e32 v171, 31, v170
	v_add_u32_e32 v172, 0x90, v162
	v_ashrrev_i32_e32 v173, 31, v172
	v_add_u32_e32 v174, 0xa0, v162
	v_ashrrev_i32_e32 v175, 31, v174
	v_add_u32_e32 v176, 0xb0, v162
	v_ashrrev_i32_e32 v177, 31, v176
	v_mad_i64_i32 v[162:163], s[26:27], v162, s30, 0
	v_lshl_add_u64 v[162:163], v[162:163], 1, s[18:19]
	s_and_b64 vcc, exec, s[4:5]
	s_waitcnt vmcnt(0)
	v_mov_b32_e32 v154, v131
	v_mov_b32_e32 v155, v132
	v_mov_b32_e32 v131, v133
	v_pk_add_f32 v[130:131], v[154:155], v[130:131]
	s_nop 0
	v_add_f32_e32 v130, v130, v131
	v_mov_b32_e32 v131, v130
	s_nop 1
	v_permlane16_swap_b32 v131, v130
	s_waitcnt lgkmcnt(0)
	v_add_f32_e32 v130, v130, v131
	v_mov_b32_e32 v131, v130
	s_nop 1
	v_permlane32_swap_b32 v131, v130
	s_waitcnt lgkmcnt(0)
	v_add_f32_e32 v130, v130, v131
	v_fmamk_f32 v130, v130, 0x3a800000, v231
	v_rsq_f32_e32 v148, v130
	s_nop 1
	ds_write_b32 v210, v148
	s_nop 1
	v_pk_mul_f32 v[128:129], v[128:129], v[148:149] op_sel_hi:[1,0]
	v_pk_mul_f32 v[126:127], v[126:127], v[148:149] op_sel_hi:[1,0]
	v_pk_mul_f32 v[120:121], v[120:121], v[148:149] op_sel_hi:[1,0]
	v_pk_mul_f32 v[118:119], v[118:119], v[148:149] op_sel_hi:[1,0]
	v_add_f32_e32 v130, v181, v180
	v_add_f32_e32 v131, v182, v183
	s_nop 0
	v_add_f32_e32 v130, v130, v131
	v_mov_b32_e32 v131, v130
	s_nop 1
	v_permlane16_swap_b32 v131, v130
	s_waitcnt lgkmcnt(0)
	v_add_f32_e32 v130, v130, v131
	v_mov_b32_e32 v131, v130
	s_nop 1
	v_permlane32_swap_b32 v131, v130
	s_waitcnt lgkmcnt(0)
	v_add_f32_e32 v130, v130, v131
	v_fmamk_f32 v130, v130, 0x3a800000, v231
	v_rsq_f32_e32 v150, v130
	s_nop 1
	ds_write_b32 v210, v150 offset:64
	s_nop 1
	v_pk_mul_f32 v[112:113], v[112:113], v[150:151] op_sel_hi:[1,0]
	v_pk_mul_f32 v[110:111], v[110:111], v[150:151] op_sel_hi:[1,0]
	v_pk_mul_f32 v[104:105], v[104:105], v[150:151] op_sel_hi:[1,0]
	v_pk_mul_f32 v[102:103], v[102:103], v[150:151] op_sel_hi:[1,0]
	v_add_f32_e32 v130, v185, v184
	v_add_f32_e32 v131, v186, v187
	s_nop 0
	v_add_f32_e32 v130, v130, v131
	v_mov_b32_e32 v131, v130
	s_nop 1
	v_permlane16_swap_b32 v131, v130
	s_waitcnt lgkmcnt(0)
	v_add_f32_e32 v130, v130, v131
	v_mov_b32_e32 v131, v130
	s_nop 1
	v_permlane32_swap_b32 v131, v130
	s_waitcnt lgkmcnt(0)
	v_add_f32_e32 v130, v130, v131
	v_fmamk_f32 v130, v130, 0x3a800000, v231
	v_rsq_f32_e32 v152, v130
	s_nop 1
	ds_write_b32 v210, v152 offset:128
	s_nop 1
	v_pk_mul_f32 v[96:97], v[96:97], v[152:153] op_sel_hi:[1,0]
	v_pk_mul_f32 v[94:95], v[94:95], v[152:153] op_sel_hi:[1,0]
	v_pk_mul_f32 v[88:89], v[88:89], v[152:153] op_sel_hi:[1,0]
	v_pk_mul_f32 v[86:87], v[86:87], v[152:153] op_sel_hi:[1,0]
	v_add_f32_e32 v130, v189, v188
	v_add_f32_e32 v131, v190, v191
	s_nop 0
	v_add_f32_e32 v130, v130, v131
	v_mov_b32_e32 v131, v130
	s_nop 1
	v_permlane16_swap_b32 v131, v130
	s_waitcnt lgkmcnt(0)
	v_add_f32_e32 v130, v130, v131
	v_mov_b32_e32 v131, v130
	s_nop 1
	v_permlane32_swap_b32 v131, v130
	s_waitcnt lgkmcnt(0)
	v_add_f32_e32 v130, v130, v131
	v_fmamk_f32 v130, v130, 0x3a800000, v231
	v_rsq_f32_e32 v154, v130
	s_nop 1
	ds_write_b32 v210, v154 offset:192
	s_nop 1
	v_pk_mul_f32 v[80:81], v[80:81], v[154:155] op_sel_hi:[1,0]
	v_pk_mul_f32 v[78:79], v[78:79], v[154:155] op_sel_hi:[1,0]
	v_pk_mul_f32 v[72:73], v[72:73], v[154:155] op_sel_hi:[1,0]
	v_pk_mul_f32 v[70:71], v[70:71], v[154:155] op_sel_hi:[1,0]
	v_add_f32_e32 v130, v193, v192
	v_add_f32_e32 v131, v194, v195
	s_nop 0
	v_add_f32_e32 v130, v130, v131
	v_mov_b32_e32 v131, v130
	s_nop 1
	v_permlane16_swap_b32 v131, v130
	s_waitcnt lgkmcnt(0)
	v_add_f32_e32 v130, v130, v131
	v_mov_b32_e32 v131, v130
	s_nop 1
	v_permlane32_swap_b32 v131, v130
	s_waitcnt lgkmcnt(0)
	v_add_f32_e32 v130, v130, v131
	v_fmamk_f32 v130, v130, 0x3a800000, v231
	v_rsq_f32_e32 v156, v130
	s_nop 1
	ds_write_b32 v210, v156 offset:512
	s_nop 1
	v_pk_mul_f32 v[64:65], v[64:65], v[156:157] op_sel_hi:[1,0]
	v_pk_mul_f32 v[62:63], v[62:63], v[156:157] op_sel_hi:[1,0]
	v_pk_mul_f32 v[56:57], v[56:57], v[156:157] op_sel_hi:[1,0]
	v_pk_mul_f32 v[54:55], v[54:55], v[156:157] op_sel_hi:[1,0]
	v_add_f32_e32 v130, v197, v196
	v_add_f32_e32 v131, v198, v199
	s_nop 0
	v_add_f32_e32 v130, v130, v131
	v_mov_b32_e32 v131, v130
	s_nop 1
	v_permlane16_swap_b32 v131, v130
	s_waitcnt lgkmcnt(0)
	v_add_f32_e32 v130, v130, v131
	v_mov_b32_e32 v131, v130
	s_nop 1
	v_permlane32_swap_b32 v131, v130
	s_waitcnt lgkmcnt(0)
; __device__ __forceinline__ unsigned cvt_pk_bf16(float lo, float hi) { unsigned r; asm volatile("v_cvt_pk_bf16_f32 %0, %1, %2" : "=v"(r) : "v"(lo), "v"(hi)); return r; }
; __device__ __forceinline__ float row_rstd16_coop(const float* ssq, int row, int fq, float inv_n) {
;     const f32x4 a = *(const f32x4*)(ssq + (size_t)row * 16 + fq * 4);
;     float s = (a[0] + a[1]) + (a[2] + a[3]);
;     s += __shfl_xor(s, 16); s += __shfl_xor(s, 32);
;     return __builtin_amdgcn_rsqf(s * inv_n + EPS);
; }
;     __device__ __forceinline__ void operator()(const f32x4 (&acc)[2][2][4][2], const Unit& u, int wr, int wc, int fr, int fq) const {
;     ...
;         for (int ai = 0; ai < 2; ++ai)
; #pragma unroll
;             for (int m = 0; m < 4; ++m) {
;                 const int row = row0 + ai * HALF + m * 16;
;                 const float rs = rsv[ai][m];
;                 bf16_t* rowp = O + (size_t)row * ldc + col0;
; #pragma unroll
;                 for (int bj = 0; bj < 2; ++bj) {
;                     const f32x4 v0 = acc[ai][bj][m][0] * rs, v1 = acc[ai][bj][m][1] * rs;
;                     u32x4 w; w.x = cvt_pk_bf16(v0[0], v0[1]); w.y = cvt_pk_bf16(v0[2], v0[3]); w.z = cvt_pk_bf16(v1[0], v1[1]); w.w = cvt_pk_bf16(v1[2], v1[3]);
;                     *(u32x4*)(rowp + bj * HALF) = w;
;                 }
	v_add_f32_e32 v130, v130, v131
	v_fmamk_f32 v130, v130, 0x3a800000, v231
	v_rsq_f32_e32 v158, v130
	s_nop 1
	ds_write_b32 v210, v158 offset:576
	s_nop 1
	v_pk_mul_f32 v[48:49], v[48:49], v[158:159] op_sel_hi:[1,0]
	v_pk_mul_f32 v[46:47], v[46:47], v[158:159] op_sel_hi:[1,0]
	v_pk_mul_f32 v[40:41], v[40:41], v[158:159] op_sel_hi:[1,0]
	v_pk_mul_f32 v[38:39], v[38:39], v[158:159] op_sel_hi:[1,0]
	v_add_f32_e32 v130, v201, v200
	v_add_f32_e32 v131, v202, v203
	s_nop 0
	v_add_f32_e32 v130, v130, v131
	v_mov_b32_e32 v131, v130
	s_nop 1
	v_permlane16_swap_b32 v131, v130
	s_waitcnt lgkmcnt(0)
	v_add_f32_e32 v130, v130, v131
	v_mov_b32_e32 v131, v130
	s_nop 1
	v_permlane32_swap_b32 v131, v130
	s_waitcnt lgkmcnt(0)
	v_add_f32_e32 v130, v130, v131
	v_fmamk_f32 v130, v130, 0x3a800000, v231
	v_rsq_f32_e32 v160, v130
	s_nop 1
	ds_write_b32 v210, v160 offset:640
	s_nop 1
	v_mov_b32_e32 v130, v204
	v_mov_b32_e32 v131, v205
	v_mov_b32_e32 v132, v206
	v_mov_b32_e32 v133, v207
	v_pk_mul_f32 v[32:33], v[32:33], v[160:161] op_sel_hi:[1,0]
	v_pk_mul_f32 v[30:31], v[30:31], v[160:161] op_sel_hi:[1,0]
	v_pk_mul_f32 v[24:25], v[24:25], v[160:161] op_sel_hi:[1,0]
	v_pk_mul_f32 v[22:23], v[22:23], v[160:161] op_sel_hi:[1,0]
	s_waitcnt vmcnt(0)
	v_mov_b32_e32 v179, v132
	v_lshl_or_b32 v132, s54, 8, v151
	v_mov_b32_e32 v178, v131
	v_mov_b32_e32 v131, v133
	v_ashrrev_i32_e32 v133, 31, v132
	v_lshlrev_b64 v[132:133], 1, v[132:133]
	v_pk_add_f32 v[130:131], v[178:179], v[130:131]
	v_lshl_add_u64 v[162:163], v[162:163], 0, v[132:133]
	v_pk_mul_f32 v[178:179], v[124:125], v[148:149] op_sel_hi:[1,0]
	v_pk_mul_f32 v[124:125], v[122:123], v[148:149] op_sel_hi:[1,0]
	v_cvt_pk_bf16_f32 v122, v126, v127
	v_cvt_pk_bf16_f32 v123, v128, v129
	v_add_f32_e32 v130, v130, v131
	v_cvt_pk_bf16_f32 v124, v124, v125
	v_cvt_pk_bf16_f32 v125, v178, v179
	global_store_dwordx4 v[162:163], v[122:125], off
	v_mov_b32_e32 v131, v130
	s_nop 1
	v_permlane16_swap_b32 v131, v130
	s_waitcnt lgkmcnt(0)
	v_add_f32_e32 v130, v130, v131
	v_pk_mul_f32 v[122:123], v[116:117], v[148:149] op_sel_hi:[1,0]
	v_pk_mul_f32 v[116:117], v[114:115], v[148:149] op_sel_hi:[1,0]
	v_cvt_pk_bf16_f32 v114, v118, v119
	v_cvt_pk_bf16_f32 v115, v120, v121
	v_mov_b32_e32 v131, v130
	s_nop 1
	v_permlane32_swap_b32 v131, v130
	v_cvt_pk_bf16_f32 v116, v116, v117
	v_cvt_pk_bf16_f32 v117, v122, v123
	global_store_dwordx4 v[162:163], v[114:117], off offset:256
	s_waitcnt lgkmcnt(0)
	v_add_f32_e32 v130, v130, v131
	v_mad_i64_i32 v[114:115], s[26:27], v164, s30, 0
	v_lshl_add_u64 v[114:115], v[114:115], 1, s[18:19]
	v_lshl_add_u64 v[114:115], v[114:115], 0, v[132:133]
	v_pk_mul_f32 v[116:117], v[108:109], v[150:151] op_sel_hi:[1,0]
	v_pk_mul_f32 v[108:109], v[106:107], v[150:151] op_sel_hi:[1,0]
	v_cvt_pk_bf16_f32 v106, v110, v111
	v_cvt_pk_bf16_f32 v107, v112, v113
	v_fmamk_f32 v130, v130, 0x3a800000, v231
	v_cvt_pk_bf16_f32 v108, v108, v109
	v_cvt_pk_bf16_f32 v109, v116, v117
	global_store_dwordx4 v[114:115], v[106:109], off
	v_rsq_f32_e32 v130, v130
	s_nop 1
	ds_write_b32 v210, v130 offset:704
	s_branch .Lmy_rs_join_1
.Lmy_rs_cached_1:
	v_lshlrev_b32_e32 v210, 2, v1
	v_add_u32_e32 v210, 0x21000, v210
	ds_read_b32 v180, v210
	ds_read_b32 v184, v210 offset:64
	ds_read_b32 v188, v210 offset:128
	ds_read_b32 v192, v210 offset:192
	ds_read_b32 v196, v210 offset:512
	ds_read_b32 v200, v210 offset:576
	ds_read_b32 v204, v210 offset:640
	ds_read_b32 v208, v210 offset:704
	s_waitcnt lgkmcnt(0)
	v_lshl_add_u32 v162, s55, 8, v1
	v_ashrrev_i32_e32 v163, 31, v162
	v_lshlrev_b64 v[130:131], 6, v[162:163]
	v_lshl_add_u64 v[130:131], v[142:143], 0, v[130:131]
	v_or_b32_e32 v164, 16, v162
	v_ashrrev_i32_e32 v165, 31, v164
	v_or_b32_e32 v166, 32, v162
	v_ashrrev_i32_e32 v167, 31, v166
	v_or_b32_e32 v168, 48, v162
	v_ashrrev_i32_e32 v169, 31, v168
	v_add_u32_e32 v170, 0x80, v162
	v_ashrrev_i32_e32 v171, 31, v170
	v_add_u32_e32 v172, 0x90, v162
	v_ashrrev_i32_e32 v173, 31, v172
	v_add_u32_e32 v174, 0xa0, v162
	v_ashrrev_i32_e32 v175, 31, v174
	v_add_u32_e32 v176, 0xb0, v162
	v_ashrrev_i32_e32 v177, 31, v176
	v_mad_i64_i32 v[162:163], s[26:27], v162, s30, 0
	v_lshl_add_u64 v[162:163], v[162:163], 1, s[18:19]
	s_and_b64 vcc, exec, s[4:5]
	v_mov_b32_e32 v154, v131
	v_mov_b32_e32 v155, v132
	v_mov_b32_e32 v131, v133
	v_pk_add_f32 v[130:131], v[154:155], v[130:131]
	s_nop 0
	v_add_f32_e32 v130, v130, v131
	v_mov_b32_e32 v131, v130
	s_nop 1
	v_permlane16_swap_b32 v131, v130
	s_waitcnt lgkmcnt(0)
	v_add_f32_e32 v130, v130, v131
	v_mov_b32_e32 v131, v130
	s_nop 1
	v_permlane32_swap_b32 v131, v130
	s_waitcnt lgkmcnt(0)
	v_add_f32_e32 v130, v130, v131
	v_fmamk_f32 v130, v130, 0x3a800000, v231
	v_mov_b32_e32 v148, v180
	s_nop 1
	v_pk_mul_f32 v[128:129], v[128:129], v[148:149] op_sel_hi:[1,0]
	v_pk_mul_f32 v[126:127], v[126:127], v[148:149] op_sel_hi:[1,0]
	v_pk_mul_f32 v[120:121], v[120:121], v[148:149] op_sel_hi:[1,0]
	v_pk_mul_f32 v[118:119], v[118:119], v[148:149] op_sel_hi:[1,0]
	v_add_f32_e32 v130, v181, v180
	v_add_f32_e32 v131, v182, v183
	s_nop 0
	v_add_f32_e32 v130, v130, v131
	v_mov_b32_e32 v131, v130
	s_nop 1
	v_permlane16_swap_b32 v131, v130
	s_waitcnt lgkmcnt(0)
	v_add_f32_e32 v130, v130, v131
	v_mov_b32_e32 v131, v130
	s_nop 1
	v_permlane32_swap_b32 v131, v130
	s_waitcnt lgkmcnt(0)
	v_add_f32_e32 v130, v130, v131
	v_fmamk_f32 v130, v130, 0x3a800000, v231
	v_mov_b32_e32 v150, v184
	s_nop 1
	v_pk_mul_f32 v[112:113], v[112:113], v[150:151] op_sel_hi:[1,0]
	v_pk_mul_f32 v[110:111], v[110:111], v[150:151] op_sel_hi:[1,0]
	v_pk_mul_f32 v[104:105], v[104:105], v[150:151] op_sel_hi:[1,0]
	v_pk_mul_f32 v[102:103], v[102:103], v[150:151] op_sel_hi:[1,0]
	v_add_f32_e32 v130, v185, v184
	v_add_f32_e32 v131, v186, v187
	s_nop 0
	v_add_f32_e32 v130, v130, v131
	v_mov_b32_e32 v131, v130
	s_nop 1
	v_permlane16_swap_b32 v131, v130
	s_waitcnt lgkmcnt(0)
; __device__ __forceinline__ unsigned cvt_pk_bf16(float lo, float hi) { unsigned r; asm volatile("v_cvt_pk_bf16_f32 %0, %1, %2" : "=v"(r) : "v"(lo), "v"(hi)); return r; }
; __device__ __forceinline__ float row_rstd16_coop(const float* ssq, int row, int fq, float inv_n) {
;     const f32x4 a = *(const f32x4*)(ssq + (size_t)row * 16 + fq * 4);
;     float s = (a[0] + a[1]) + (a[2] + a[3]);
;     s += __shfl_xor(s, 16); s += __shfl_xor(s, 32);
;     return __builtin_amdgcn_rsqf(s * inv_n + EPS);
; }
;     __device__ __forceinline__ void operator()(const f32x4 (&acc)[2][2][4][2], const Unit& u, int wr, int wc, int fr, int fq) const {
;         const int row0 = u.pm * BM + wr * 64 + fr, col0 = u.pn * BM + wc * 32 + 8 * fq;
;         float rsv[2][4];
; #pragma unroll
;         for (int ai = 0; ai < 2; ++ai) {
; #pragma unroll
;             for (int m = 0; m < 4; ++m) rsv[ai][m] = ssq ? row_rstd16_coop(ssq, row0 + ai * HALF + m * 16, fq, 1.0f / 1024.0f) : 1.0f;
;         }
; #pragma unroll
;         for (int ai = 0; ai < 2; ++ai)
; #pragma unroll
;             for (int m = 0; m < 4; ++m) {
;                 const int row = row0 + ai * HALF + m * 16;
;                 const float rs = rsv[ai][m];
;                 bf16_t* rowp = O + (size_t)row * ldc + col0;
; #pragma unroll
;                 for (int bj = 0; bj < 2; ++bj) {
;                     const f32x4 v0 = acc[ai][bj][m][0] * rs, v1 = acc[ai][bj][m][1] * rs;
;                     u32x4 w; w.x = cvt_pk_bf16(v0[0], v0[1]); w.y = cvt_pk_bf16(v0[2], v0[3]); w.z = cvt_pk_bf16(v1[0], v1[1]); w.w = cvt_pk_bf16(v1[2], v1[3]);
;                     *(u32x4*)(rowp + bj * HALF) = w;
	v_add_f32_e32 v130, v130, v131
	v_mov_b32_e32 v131, v130
	s_nop 1
	v_permlane32_swap_b32 v131, v130
	s_waitcnt lgkmcnt(0)
	v_add_f32_e32 v130, v130, v131
	v_fmamk_f32 v130, v130, 0x3a800000, v231
	v_mov_b32_e32 v152, v188
	s_nop 1
	v_pk_mul_f32 v[96:97], v[96:97], v[152:153] op_sel_hi:[1,0]
	v_pk_mul_f32 v[94:95], v[94:95], v[152:153] op_sel_hi:[1,0]
	v_pk_mul_f32 v[88:89], v[88:89], v[152:153] op_sel_hi:[1,0]
	v_pk_mul_f32 v[86:87], v[86:87], v[152:153] op_sel_hi:[1,0]
	v_add_f32_e32 v130, v189, v188
	v_add_f32_e32 v131, v190, v191
	s_nop 0
	v_add_f32_e32 v130, v130, v131
	v_mov_b32_e32 v131, v130
	s_nop 1
	v_permlane16_swap_b32 v131, v130
	s_waitcnt lgkmcnt(0)
	v_add_f32_e32 v130, v130, v131
	v_mov_b32_e32 v131, v130
	s_nop 1
	v_permlane32_swap_b32 v131, v130
	s_waitcnt lgkmcnt(0)
	v_add_f32_e32 v130, v130, v131
	v_fmamk_f32 v130, v130, 0x3a800000, v231
	v_mov_b32_e32 v154, v192
	s_nop 1
	v_pk_mul_f32 v[80:81], v[80:81], v[154:155] op_sel_hi:[1,0]
	v_pk_mul_f32 v[78:79], v[78:79], v[154:155] op_sel_hi:[1,0]
	v_pk_mul_f32 v[72:73], v[72:73], v[154:155] op_sel_hi:[1,0]
	v_pk_mul_f32 v[70:71], v[70:71], v[154:155] op_sel_hi:[1,0]
	v_add_f32_e32 v130, v193, v192
	v_add_f32_e32 v131, v194, v195
	s_nop 0
	v_add_f32_e32 v130, v130, v131
	v_mov_b32_e32 v131, v130
	s_nop 1
	v_permlane16_swap_b32 v131, v130
	s_waitcnt lgkmcnt(0)
	v_add_f32_e32 v130, v130, v131
	v_mov_b32_e32 v131, v130
	s_nop 1
	v_permlane32_swap_b32 v131, v130
	s_waitcnt lgkmcnt(0)
	v_add_f32_e32 v130, v130, v131
	v_fmamk_f32 v130, v130, 0x3a800000, v231
	v_mov_b32_e32 v156, v196
	s_nop 1
	v_pk_mul_f32 v[64:65], v[64:65], v[156:157] op_sel_hi:[1,0]
	v_pk_mul_f32 v[62:63], v[62:63], v[156:157] op_sel_hi:[1,0]
	v_pk_mul_f32 v[56:57], v[56:57], v[156:157] op_sel_hi:[1,0]
	v_pk_mul_f32 v[54:55], v[54:55], v[156:157] op_sel_hi:[1,0]
	v_add_f32_e32 v130, v197, v196
	v_add_f32_e32 v131, v198, v199
	s_nop 0
	v_add_f32_e32 v130, v130, v131
	v_mov_b32_e32 v131, v130
	s_nop 1
	v_permlane16_swap_b32 v131, v130
	s_waitcnt lgkmcnt(0)
	v_add_f32_e32 v130, v130, v131
	v_mov_b32_e32 v131, v130
	s_nop 1
	v_permlane32_swap_b32 v131, v130
	s_waitcnt lgkmcnt(0)
	v_add_f32_e32 v130, v130, v131
	v_fmamk_f32 v130, v130, 0x3a800000, v231
	v_mov_b32_e32 v158, v200
	s_nop 1
	v_pk_mul_f32 v[48:49], v[48:49], v[158:159] op_sel_hi:[1,0]
	v_pk_mul_f32 v[46:47], v[46:47], v[158:159] op_sel_hi:[1,0]
	v_pk_mul_f32 v[40:41], v[40:41], v[158:159] op_sel_hi:[1,0]
	v_pk_mul_f32 v[38:39], v[38:39], v[158:159] op_sel_hi:[1,0]
	v_add_f32_e32 v130, v201, v200
	v_add_f32_e32 v131, v202, v203
	s_nop 0
	v_add_f32_e32 v130, v130, v131
	v_mov_b32_e32 v131, v130
	s_nop 1
	v_permlane16_swap_b32 v131, v130
	s_waitcnt lgkmcnt(0)
	v_add_f32_e32 v130, v130, v131
	v_mov_b32_e32 v131, v130
	s_nop 1
	v_permlane32_swap_b32 v131, v130
	s_waitcnt lgkmcnt(0)
	v_add_f32_e32 v130, v130, v131
	v_fmamk_f32 v130, v130, 0x3a800000, v231
	v_mov_b32_e32 v160, v204
	s_nop 1
	v_mov_b32_e32 v130, v204
	v_mov_b32_e32 v131, v205
	v_mov_b32_e32 v132, v206
	v_mov_b32_e32 v133, v207
	v_pk_mul_f32 v[32:33], v[32:33], v[160:161] op_sel_hi:[1,0]
	v_pk_mul_f32 v[30:31], v[30:31], v[160:161] op_sel_hi:[1,0]
	v_pk_mul_f32 v[24:25], v[24:25], v[160:161] op_sel_hi:[1,0]
	v_pk_mul_f32 v[22:23], v[22:23], v[160:161] op_sel_hi:[1,0]
	v_mov_b32_e32 v179, v132
	v_lshl_or_b32 v132, s54, 8, v151
	v_mov_b32_e32 v178, v131
	v_mov_b32_e32 v131, v133
	v_ashrrev_i32_e32 v133, 31, v132
	v_lshlrev_b64 v[132:133], 1, v[132:133]
	v_pk_add_f32 v[130:131], v[178:179], v[130:131]
	v_lshl_add_u64 v[162:163], v[162:163], 0, v[132:133]
	v_pk_mul_f32 v[178:179], v[124:125], v[148:149] op_sel_hi:[1,0]
	v_pk_mul_f32 v[124:125], v[122:123], v[148:149] op_sel_hi:[1,0]
	v_cvt_pk_bf16_f32 v122, v126, v127
	v_cvt_pk_bf16_f32 v123, v128, v129
	v_add_f32_e32 v130, v130, v131
	v_cvt_pk_bf16_f32 v124, v124, v125
	v_cvt_pk_bf16_f32 v125, v178, v179
	global_store_dwordx4 v[162:163], v[122:125], off
	v_mov_b32_e32 v131, v130
	s_nop 1
	v_permlane16_swap_b32 v131, v130
	s_waitcnt lgkmcnt(0)
	v_add_f32_e32 v130, v130, v131
	v_pk_mul_f32 v[122:123], v[116:117], v[148:149] op_sel_hi:[1,0]
	v_pk_mul_f32 v[116:117], v[114:115], v[148:149] op_sel_hi:[1,0]
	v_cvt_pk_bf16_f32 v114, v118, v119
	v_cvt_pk_bf16_f32 v115, v120, v121
	v_mov_b32_e32 v131, v130
	s_nop 1
	v_permlane32_swap_b32 v131, v130
	v_cvt_pk_bf16_f32 v116, v116, v117
	v_cvt_pk_bf16_f32 v117, v122, v123
	global_store_dwordx4 v[162:163], v[114:117], off offset:256
	s_waitcnt lgkmcnt(0)
	v_add_f32_e32 v130, v130, v131
	v_mad_i64_i32 v[114:115], s[26:27], v164, s30, 0
	v_lshl_add_u64 v[114:115], v[114:115], 1, s[18:19]
	v_lshl_add_u64 v[114:115], v[114:115], 0, v[132:133]
	v_pk_mul_f32 v[116:117], v[108:109], v[150:151] op_sel_hi:[1,0]
	v_pk_mul_f32 v[108:109], v[106:107], v[150:151] op_sel_hi:[1,0]
	v_cvt_pk_bf16_f32 v106, v110, v111
	v_cvt_pk_bf16_f32 v107, v112, v113
	v_fmamk_f32 v130, v130, 0x3a800000, v231
	v_cvt_pk_bf16_f32 v108, v108, v109
	v_cvt_pk_bf16_f32 v109, v116, v117
	global_store_dwordx4 v[114:115], v[106:109], off
	v_mov_b32_e32 v130, v208
; __device__ __forceinline__ unsigned cvt_pk_bf16(float lo, float hi) { unsigned r; asm volatile("v_cvt_pk_bf16_f32 %0, %1, %2" : "=v"(r) : "v"(lo), "v"(hi)); return r; }
;     __device__ __forceinline__ void operator()(const f32x4 (&acc)[2][2][4][2], const Unit& u, int wr, int wc, int fr, int fq) const {
;     ...
; #pragma unroll
;         for (int ai = 0; ai < 2; ++ai)
; #pragma unroll
;             for (int m = 0; m < 4; ++m) {
;                 const int row = row0 + ai * HALF + m * 16;
;                 const float rs = rsv[ai][m];
;                 bf16_t* rowp = O + (size_t)row * ldc + col0;
; #pragma unroll
;                 for (int bj = 0; bj < 2; ++bj) {
;                     const f32x4 v0 = acc[ai][bj][m][0] * rs, v1 = acc[ai][bj][m][1] * rs;
;                     u32x4 w; w.x = cvt_pk_bf16(v0[0], v0[1]); w.y = cvt_pk_bf16(v0[2], v0[3]); w.z = cvt_pk_bf16(v1[0], v1[1]); w.w = cvt_pk_bf16(v1[2], v1[3]);
;                     *(u32x4*)(rowp + bj * HALF) = w;
;                 }
;             }
.Lmy_rs_join_1:
	s_nop 0
	v_pk_mul_f32 v[106:107], v[100:101], v[150:151] op_sel_hi:[1,0]
	v_pk_mul_f32 v[100:101], v[98:99], v[150:151] op_sel_hi:[1,0]
	v_cvt_pk_bf16_f32 v98, v102, v103
	v_cvt_pk_bf16_f32 v99, v104, v105
	v_pk_mul_f32 v[16:17], v[16:17], v[130:131] op_sel_hi:[1,0]
	v_cvt_pk_bf16_f32 v100, v100, v101
	v_cvt_pk_bf16_f32 v101, v106, v107
	global_store_dwordx4 v[114:115], v[98:101], off offset:256
	v_pk_mul_f32 v[14:15], v[14:15], v[130:131] op_sel_hi:[1,0]
	v_pk_mul_f32 v[8:9], v[8:9], v[130:131] op_sel_hi:[1,0]
	v_mad_i64_i32 v[98:99], s[26:27], v166, s30, 0
	v_lshl_add_u64 v[98:99], v[98:99], 1, s[18:19]
	v_lshl_add_u64 v[98:99], v[98:99], 0, v[132:133]
	v_pk_mul_f32 v[100:101], v[92:93], v[152:153] op_sel_hi:[1,0]
	v_pk_mul_f32 v[92:93], v[90:91], v[152:153] op_sel_hi:[1,0]
	v_cvt_pk_bf16_f32 v90, v94, v95
	v_cvt_pk_bf16_f32 v91, v96, v97
	v_pk_mul_f32 v[6:7], v[6:7], v[130:131] op_sel_hi:[1,0]
	v_cvt_pk_bf16_f32 v92, v92, v93
	v_cvt_pk_bf16_f32 v93, v100, v101
	global_store_dwordx4 v[98:99], v[90:93], off
	s_nop 1
	v_pk_mul_f32 v[90:91], v[84:85], v[152:153] op_sel_hi:[1,0]
	v_pk_mul_f32 v[84:85], v[82:83], v[152:153] op_sel_hi:[1,0]
	v_cvt_pk_bf16_f32 v82, v86, v87
	v_cvt_pk_bf16_f32 v83, v88, v89
	s_nop 0
	v_cvt_pk_bf16_f32 v84, v84, v85
	v_cvt_pk_bf16_f32 v85, v90, v91
	global_store_dwordx4 v[98:99], v[82:85], off offset:256
	s_nop 1
	v_mad_i64_i32 v[82:83], s[26:27], v168, s30, 0
	v_lshl_add_u64 v[82:83], v[82:83], 1, s[18:19]
	v_lshl_add_u64 v[82:83], v[82:83], 0, v[132:133]
	v_pk_mul_f32 v[84:85], v[76:77], v[154:155] op_sel_hi:[1,0]
	v_pk_mul_f32 v[76:77], v[74:75], v[154:155] op_sel_hi:[1,0]
	v_cvt_pk_bf16_f32 v74, v78, v79
	v_cvt_pk_bf16_f32 v75, v80, v81
	s_nop 0
	v_cvt_pk_bf16_f32 v76, v76, v77
	v_cvt_pk_bf16_f32 v77, v84, v85
	global_store_dwordx4 v[82:83], v[74:77], off
	s_nop 1
	v_pk_mul_f32 v[74:75], v[68:69], v[154:155] op_sel_hi:[1,0]
	v_pk_mul_f32 v[68:69], v[66:67], v[154:155] op_sel_hi:[1,0]
	v_cvt_pk_bf16_f32 v66, v70, v71
	v_cvt_pk_bf16_f32 v67, v72, v73
	s_nop 0
	v_cvt_pk_bf16_f32 v68, v68, v69
	v_cvt_pk_bf16_f32 v69, v74, v75
	global_store_dwordx4 v[82:83], v[66:69], off offset:256
	s_nop 1
	v_mad_i64_i32 v[66:67], s[26:27], v170, s30, 0
	v_lshl_add_u64 v[66:67], v[66:67], 1, s[18:19]
	v_lshl_add_u64 v[66:67], v[66:67], 0, v[132:133]
	v_pk_mul_f32 v[68:69], v[60:61], v[156:157] op_sel_hi:[1,0]
	v_pk_mul_f32 v[60:61], v[58:59], v[156:157] op_sel_hi:[1,0]
	v_cvt_pk_bf16_f32 v58, v62, v63
	v_cvt_pk_bf16_f32 v59, v64, v65
	s_nop 0
	v_cvt_pk_bf16_f32 v60, v60, v61
	v_cvt_pk_bf16_f32 v61, v68, v69
	global_store_dwordx4 v[66:67], v[58:61], off
	s_nop 1
	v_pk_mul_f32 v[58:59], v[52:53], v[156:157] op_sel_hi:[1,0]
	v_pk_mul_f32 v[52:53], v[50:51], v[156:157] op_sel_hi:[1,0]
	v_cvt_pk_bf16_f32 v50, v54, v55
	v_cvt_pk_bf16_f32 v51, v56, v57
	s_nop 0
	v_cvt_pk_bf16_f32 v52, v52, v53
	v_cvt_pk_bf16_f32 v53, v58, v59
	global_store_dwordx4 v[66:67], v[50:53], off offset:256
	s_nop 1
	v_mad_i64_i32 v[50:51], s[26:27], v172, s30, 0
	v_lshl_add_u64 v[50:51], v[50:51], 1, s[18:19]
	v_lshl_add_u64 v[50:51], v[50:51], 0, v[132:133]
	v_pk_mul_f32 v[52:53], v[44:45], v[158:159] op_sel_hi:[1,0]
	v_pk_mul_f32 v[44:45], v[42:43], v[158:159] op_sel_hi:[1,0]
	v_cvt_pk_bf16_f32 v42, v46, v47
	v_cvt_pk_bf16_f32 v43, v48, v49
	s_nop 0
	v_cvt_pk_bf16_f32 v44, v44, v45
	v_cvt_pk_bf16_f32 v45, v52, v53
	global_store_dwordx4 v[50:51], v[42:45], off
	s_nop 1
	v_pk_mul_f32 v[42:43], v[36:37], v[158:159] op_sel_hi:[1,0]
	v_pk_mul_f32 v[36:37], v[34:35], v[158:159] op_sel_hi:[1,0]
	v_cvt_pk_bf16_f32 v34, v38, v39
	v_cvt_pk_bf16_f32 v35, v40, v41
	s_nop 0
	v_cvt_pk_bf16_f32 v36, v36, v37
	v_cvt_pk_bf16_f32 v37, v42, v43
	global_store_dwordx4 v[50:51], v[34:37], off offset:256
	s_nop 1
	v_mad_i64_i32 v[34:35], s[26:27], v174, s30, 0
	v_lshl_add_u64 v[34:35], v[34:35], 1, s[18:19]
	v_lshl_add_u64 v[34:35], v[34:35], 0, v[132:133]
	v_pk_mul_f32 v[36:37], v[28:29], v[160:161] op_sel_hi:[1,0]
	v_pk_mul_f32 v[28:29], v[26:27], v[160:161] op_sel_hi:[1,0]
	v_cvt_pk_bf16_f32 v26, v30, v31
	v_cvt_pk_bf16_f32 v27, v32, v33
	s_nop 0
	v_cvt_pk_bf16_f32 v28, v28, v29
	v_cvt_pk_bf16_f32 v29, v36, v37
	global_store_dwordx4 v[34:35], v[26:29], off
	s_nop 1
	v_pk_mul_f32 v[26:27], v[20:21], v[160:161] op_sel_hi:[1,0]
	v_pk_mul_f32 v[20:21], v[18:19], v[160:161] op_sel_hi:[1,0]
	v_cvt_pk_bf16_f32 v18, v22, v23
	v_cvt_pk_bf16_f32 v19, v24, v25
	s_nop 0
	v_cvt_pk_bf16_f32 v20, v20, v21
	v_cvt_pk_bf16_f32 v21, v26, v27
	global_store_dwordx4 v[34:35], v[18:21], off offset:256
	s_nop 1
	v_mad_i64_i32 v[18:19], s[26:27], v176, s30, 0
	v_lshl_add_u64 v[18:19], v[18:19], 1, s[18:19]
	v_lshl_add_u64 v[18:19], v[18:19], 0, v[132:133]
	v_pk_mul_f32 v[20:21], v[12:13], v[130:131] op_sel_hi:[1,0]
	v_pk_mul_f32 v[12:13], v[10:11], v[130:131] op_sel_hi:[1,0]
	v_cvt_pk_bf16_f32 v10, v14, v15
	v_cvt_pk_bf16_f32 v11, v16, v17
	s_mov_b64 s[26:27], -1
	v_cvt_pk_bf16_f32 v12, v12, v13
	v_cvt_pk_bf16_f32 v13, v20, v21
	global_store_dwordx4 v[18:19], v[10:13], off
	s_nop 1
	v_pk_mul_f32 v[10:11], v[4:5], v[130:131] op_sel_hi:[1,0]
	v_pk_mul_f32 v[4:5], v[2:3], v[130:131] op_sel_hi:[1,0]
	v_cvt_pk_bf16_f32 v2, v6, v7
	v_cvt_pk_bf16_f32 v3, v8, v9
	s_nop 0
	v_cvt_pk_bf16_f32 v4, v4, v5
	v_cvt_pk_bf16_f32 v5, v10, v11
	global_store_dwordx4 v[18:19], v[2:5], off offset:256
	s_cbranch_vccnz .LBB0_3333
	s_andn2_b64 vcc, exec, s[16:17]
	s_cbranch_vccnz .LBB0_3332
	s_barrier
	s_branch .LBB0_3332

; #define PG8_STAGE(bufoff, gbase, voff) do { _Pragma("unroll") for (int _i = 0; _i < 2; ++_i) \
;         __builtin_amdgcn_global_load_lds((const unsigned*)((const char*)(gbase) + (voff)[_i]), (PG8_LAS unsigned*)(lds + (bufoff) + ldsw + _i * 8192), 16, 0, 0); } while (0)
; #define PG8_WAIT_V(n) asm volatile("s_waitcnt vmcnt(" #n ")" ::: "memory")
; #define PG8_BAR __builtin_amdgcn_s_barrier()
; template <class Epi, class Sched, bool ALIGN_EPI = false, bool SP2 = false>
; __device__ __forceinline__ void gemm_phase(PG8_LAS unsigned char* lds, const Gemm g, const Sched& S, const Epi& E) {
;     ...
;     if constexpr (SP2) {
;         PG8_STAGE(PG8_SB(0, 0), cB, voffB); PG8_STAGE(PG8_SB(0, 1), cB + hstep, voffB); PG8_STAGE(PG8_SA(0, 0), cA, voffA); PG8_STAGE(PG8_SA(0, 1), cA + hstep, voffA);
;         if (wr == 1) PG8_BAR;
;         PG8_WAIT_V(2); PG8_BAR;
;         PG8_STAGE(PG8_SB(1, 0), cB + kstep, voffB); PG8_STAGE(PG8_SA(1, 0), cA + kstep, voffA); PG8_STAGE(PG8_SB(1, 1), cB + hstep + kstep, voffB);
;         PG8_WAIT_V(6); PG8_BAR;
.LBB0_4830:
	s_add_u32 s16, s0, 0x8c00000
	s_addc_u32 s17, s1, 0
	s_add_i32 m0, s40, 0x18000
	v_lshl_add_u64 v[2:3], v[2:3], 0, s[92:93]
	s_waitcnt vmcnt(2)
	s_barrier
	global_load_lds_dwordx4 v[2:3], off
	v_lshl_add_u64 v[2:3], v[4:5], 0, s[92:93]
	s_add_i32 m0, s40, 0x1a000
	s_add_i32 s44, s40, 0x8000
	global_load_lds_dwordx4 v[2:3], off
	v_lshl_add_u64 v[2:3], v[10:11], 0, s[92:93]
	s_mov_b32 m0, s44
	s_add_i32 s45, s40, 0xa000
	global_load_lds_dwordx4 v[2:3], off
	v_lshl_add_u64 v[2:3], v[12:13], 0, s[92:93]
	s_mov_b32 m0, s45
	v_bfe_u32 v4, v14, 4, 2
	global_load_lds_dwordx4 v[2:3], off
	s_add_i32 m0, s40, 0x1c000
	v_lshl_add_u64 v[2:3], v[6:7], 0, s[92:93]
	global_load_lds_dwordx4 v[2:3], off
	v_lshl_add_u64 v[2:3], v[8:9], 0, s[92:93]
	s_add_i32 m0, s40, 0x1e000
	s_lshr_b32 s5, s5, 26
	global_load_lds_dwordx4 v[2:3], off
	v_and_b32_e32 v3, 15, v14
	s_add_i32 s5, s4, s5
	v_lshlrev_b32_e32 v2, 4, v4
	v_lshlrev_b32_e32 v5, 2, v14
	s_ashr_i32 s46, s5, 6
	v_lshl_or_b32 v1, s18, 6, v3
	v_lshl_or_b32 v3, v3, 6, v2
	s_lshl_b32 s5, s18, 13
	v_and_b32_e32 v5, 32, v5
	v_bitop3_b32 v6, v3, s5, v5 bitop3:0xde
	s_lshl_b32 s5, s19, 5
	s_and_b32 s5, s5, 0x60
	s_lshl_b32 s18, s5, 7
	s_waitcnt vmcnt(0)
	v_bitop3_b32 v151, v3, s18, v5 bitop3:0xde
	v_mov_b32_e32 v3, v0
	v_lshl_add_u64 v[2:3], s[0:1], 0, v[2:3]
	s_mov_b64 s[0:1], 0x8000000
	v_lshl_add_u64 v[142:143], v[2:3], 0, s[0:1]
	v_add_u32_e32 v2, v20, v18
	s_cmp_gt_i32 s4, 63
	v_add_lshl_u32 v2, v2, v19, 1
	v_mov_b32_e32 v3, v0
	s_waitcnt vmcnt(6)
	s_cselect_b64 s[18:19], -1, 0
	s_add_i32 s47, s46, -2
	v_lshl_add_u64 v[144:145], s[10:11], 0, v[2:3]
	v_add_u32_e32 v2, v17, v15
	s_cmpk_lt_u32 s20, 0x100
	v_add_lshl_u32 v2, v2, v16, 1
	s_cselect_b64 s[20:21], -1, 0
	v_lshl_or_b32 v155, v4, 3, s5
	v_lshl_add_u64 v[146:147], s[10:11], 0, v[2:3]
	s_mov_b32 s48, 0
	v_add_u32_e32 v161, 0, v6
	s_barrier
	s_mov_b32 s32, -1
	s_branch .LBB0_4833

; __device__ __forceinline__ float row_rstd16_coop(const float* ssq, int row, int fq, float inv_n) {
;     const f32x4 a = *(const f32x4*)(ssq + (size_t)row * 16 + fq * 4);
;     float s = (a[0] + a[1]) + (a[2] + a[3]);
;     s += __shfl_xor(s, 16); s += __shfl_xor(s, 32);
;     return __builtin_amdgcn_rsqf(s * inv_n + EPS);
; }
;     __device__ __forceinline__ void operator()(const f32x4 (&acc)[2][2][4][2], const Unit& u, int wr, int wc, int fr, int fq) const {
;         const int row0 = u.pm * BM + wr * 64 + fr, col0 = u.pn * BM + wc * 32 + 8 * fq;
;         float rsv[2][4];
; #pragma unroll
;         for (int ai = 0; ai < 2; ++ai) {
; #pragma unroll
;             for (int m = 0; m < 4; ++m) rsv[ai][m] = ssq ? row_rstd16_coop(ssq, row0 + ai * HALF + m * 16, fq, 1.0f / 1024.0f) : 1.0f;
.LBB0_4848:
	s_cmp_eq_u32 s52, s32
	s_cbranch_scc1 .Lmy_rs_cached_3
	s_mov_b32 s32, s52
	v_lshlrev_b32_e32 v212, 2, v1
	v_add_u32_e32 v212, 0x21000, v212
	v_lshl_add_u32 v156, s52, 8, v1
	v_ashrrev_i32_e32 v157, 31, v156
	v_lshlrev_b64 v[130:131], 6, v[156:157]
	v_lshl_add_u64 v[130:131], v[142:143], 0, v[130:131]
	global_load_dwordx4 v[182:185], v[130:131], off offset:1024
	global_load_dwordx4 v[186:189], v[130:131], off offset:2048
	global_load_dwordx4 v[190:193], v[130:131], off offset:3072
	v_add_co_u32_e32 v210, vcc, 0x2000, v130
	s_nop 1
	v_addc_co_u32_e32 v211, vcc, 0, v131, vcc
	global_load_dwordx4 v[194:197], v[210:211], off
	global_load_dwordx4 v[198:201], v[210:211], off offset:1024
	global_load_dwordx4 v[202:205], v[210:211], off offset:2048
	global_load_dwordx4 v[206:209], v[210:211], off offset:3072
	global_load_dwordx4 v[130:133], v[130:131], off
	v_or_b32_e32 v174, 16, v156
	v_ashrrev_i32_e32 v175, 31, v174
	v_or_b32_e32 v170, 32, v156
	v_ashrrev_i32_e32 v171, 31, v170
	v_or_b32_e32 v166, 48, v156
	v_ashrrev_i32_e32 v167, 31, v166
	v_add_u32_e32 v162, 0x80, v156
	v_ashrrev_i32_e32 v163, 31, v162
	v_add_u32_e32 v158, 0x90, v156
	v_ashrrev_i32_e32 v159, 31, v158
	v_add_u32_e32 v152, 0xa0, v156
	v_ashrrev_i32_e32 v153, 31, v152
	s_and_b64 vcc, exec, s[4:5]
	s_waitcnt vmcnt(0)
	v_mov_b32_e32 v148, v131
	v_mov_b32_e32 v149, v132
	v_mov_b32_e32 v131, v133
	v_pk_add_f32 v[130:131], v[148:149], v[130:131]
	s_nop 0
	v_add_f32_e32 v130, v130, v131
	v_mov_b32_e32 v131, v130
	s_nop 1
	v_permlane16_swap_b32 v131, v130
	s_waitcnt lgkmcnt(0)
	v_add_f32_e32 v130, v130, v131
	v_mov_b32_e32 v131, v130
	s_nop 1
	v_permlane32_swap_b32 v131, v130
	s_waitcnt lgkmcnt(0)
	v_add_f32_e32 v130, v130, v131
	v_fmamk_f32 v130, v130, 0x3a800000, v231
	v_rsq_f32_e32 v176, v130
	s_nop 1
	ds_write_b32 v212, v176
	s_nop 1
	v_pk_mul_f32 v[122:123], v[122:123], v[176:177] op_sel_hi:[1,0]
	v_pk_mul_f32 v[124:125], v[124:125], v[176:177] op_sel_hi:[1,0]
	v_pk_mul_f32 v[126:127], v[126:127], v[176:177] op_sel_hi:[1,0]
	v_pk_mul_f32 v[128:129], v[128:129], v[176:177] op_sel_hi:[1,0]
	v_pk_mul_f32 v[118:119], v[118:119], v[176:177] op_sel_hi:[1,0]
	v_pk_mul_f32 v[120:121], v[120:121], v[176:177] op_sel_hi:[1,0]
	v_pk_mul_f32 v[114:115], v[114:115], v[176:177] op_sel_hi:[1,0]
	v_pk_mul_f32 v[116:117], v[116:117], v[176:177] op_sel_hi:[1,0]
	v_add_f32_e32 v130, v183, v182
	v_add_f32_e32 v131, v184, v185
	s_nop 0
	v_add_f32_e32 v130, v130, v131
	v_mov_b32_e32 v131, v130
	s_nop 1
	v_permlane16_swap_b32 v131, v130
	s_waitcnt lgkmcnt(0)
	v_add_f32_e32 v130, v130, v131
	v_mov_b32_e32 v131, v130
	s_nop 1
	v_permlane32_swap_b32 v131, v130
	s_waitcnt lgkmcnt(0)
	v_add_f32_e32 v130, v130, v131
	v_fmamk_f32 v130, v130, 0x3a800000, v231
	v_rsq_f32_e32 v172, v130
	s_nop 1
	ds_write_b32 v212, v172 offset:64
	s_nop 1
	v_pk_mul_f32 v[110:111], v[110:111], v[172:173] op_sel_hi:[1,0]
	v_pk_mul_f32 v[112:113], v[112:113], v[172:173] op_sel_hi:[1,0]
	v_pk_mul_f32 v[106:107], v[106:107], v[172:173] op_sel_hi:[1,0]
	v_pk_mul_f32 v[108:109], v[108:109], v[172:173] op_sel_hi:[1,0]
	v_pk_mul_f32 v[102:103], v[102:103], v[172:173] op_sel_hi:[1,0]
	v_pk_mul_f32 v[104:105], v[104:105], v[172:173] op_sel_hi:[1,0]
	v_pk_mul_f32 v[98:99], v[98:99], v[172:173] op_sel_hi:[1,0]
	v_pk_mul_f32 v[100:101], v[100:101], v[172:173] op_sel_hi:[1,0]
	v_add_f32_e32 v130, v187, v186
	v_add_f32_e32 v131, v188, v189
	s_nop 0
	v_add_f32_e32 v130, v130, v131
	v_mov_b32_e32 v131, v130
	s_nop 1
	v_permlane16_swap_b32 v131, v130
	s_waitcnt lgkmcnt(0)
	v_add_f32_e32 v130, v130, v131
	v_mov_b32_e32 v131, v130
	s_nop 1
	v_permlane32_swap_b32 v131, v130
	s_waitcnt lgkmcnt(0)
	v_add_f32_e32 v130, v130, v131
	v_fmamk_f32 v130, v130, 0x3a800000, v231
	v_rsq_f32_e32 v168, v130
	s_nop 1
	ds_write_b32 v212, v168 offset:128
	s_nop 1
	v_pk_mul_f32 v[94:95], v[94:95], v[168:169] op_sel_hi:[1,0]
	v_pk_mul_f32 v[96:97], v[96:97], v[168:169] op_sel_hi:[1,0]
	v_pk_mul_f32 v[90:91], v[90:91], v[168:169] op_sel_hi:[1,0]
	v_pk_mul_f32 v[92:93], v[92:93], v[168:169] op_sel_hi:[1,0]
	v_pk_mul_f32 v[86:87], v[86:87], v[168:169] op_sel_hi:[1,0]
	v_pk_mul_f32 v[88:89], v[88:89], v[168:169] op_sel_hi:[1,0]
	v_pk_mul_f32 v[82:83], v[82:83], v[168:169] op_sel_hi:[1,0]
	v_pk_mul_f32 v[84:85], v[84:85], v[168:169] op_sel_hi:[1,0]
	v_add_f32_e32 v130, v191, v190
	v_add_f32_e32 v131, v192, v193
	s_nop 0
	v_add_f32_e32 v130, v130, v131
	v_mov_b32_e32 v131, v130
	s_nop 1
	v_permlane16_swap_b32 v131, v130
	s_waitcnt lgkmcnt(0)
	v_add_f32_e32 v130, v130, v131
	v_mov_b32_e32 v131, v130
	s_nop 1
	v_permlane32_swap_b32 v131, v130
	s_waitcnt lgkmcnt(0)
	v_add_f32_e32 v130, v130, v131
	v_fmamk_f32 v130, v130, 0x3a800000, v231
	v_rsq_f32_e32 v164, v130
	s_nop 1
	ds_write_b32 v212, v164 offset:192
	s_nop 1
	v_pk_mul_f32 v[78:79], v[78:79], v[164:165] op_sel_hi:[1,0]
	v_pk_mul_f32 v[80:81], v[80:81], v[164:165] op_sel_hi:[1,0]
	v_pk_mul_f32 v[74:75], v[74:75], v[164:165] op_sel_hi:[1,0]
	v_pk_mul_f32 v[76:77], v[76:77], v[164:165] op_sel_hi:[1,0]
	v_pk_mul_f32 v[70:71], v[70:71], v[164:165] op_sel_hi:[1,0]
	v_pk_mul_f32 v[72:73], v[72:73], v[164:165] op_sel_hi:[1,0]
	v_pk_mul_f32 v[66:67], v[66:67], v[164:165] op_sel_hi:[1,0]
	v_pk_mul_f32 v[68:69], v[68:69], v[164:165] op_sel_hi:[1,0]
	v_add_f32_e32 v130, v195, v194
	v_add_f32_e32 v131, v196, v197
	s_nop 0
	v_add_f32_e32 v130, v130, v131
	v_mov_b32_e32 v131, v130
	s_nop 1
	v_permlane16_swap_b32 v131, v130
	s_waitcnt lgkmcnt(0)
	v_add_f32_e32 v130, v130, v131
	v_mov_b32_e32 v131, v130
	s_nop 1
	v_permlane32_swap_b32 v131, v130
	s_waitcnt lgkmcnt(0)
; __device__ __forceinline__ float row_rstd16_coop(const float* ssq, int row, int fq, float inv_n) {
;     const f32x4 a = *(const f32x4*)(ssq + (size_t)row * 16 + fq * 4);
;     float s = (a[0] + a[1]) + (a[2] + a[3]);
;     s += __shfl_xor(s, 16); s += __shfl_xor(s, 32);
;     return __builtin_amdgcn_rsqf(s * inv_n + EPS);
; }
;     __device__ __forceinline__ void operator()(const f32x4 (&acc)[2][2][4][2], const Unit& u, int wr, int wc, int fr, int fq) const {
;         const int row0 = u.pm * BM + wr * 64 + fr, col0 = u.pn * BM + wc * 32 + 8 * fq;
;         float rsv[2][4];
; #pragma unroll
;         for (int ai = 0; ai < 2; ++ai) {
; #pragma unroll
;             for (int m = 0; m < 4; ++m) rsv[ai][m] = ssq ? row_rstd16_coop(ssq, row0 + ai * HALF + m * 16, fq, 1.0f / 1024.0f) : 1.0f;
	v_add_f32_e32 v130, v130, v131
	v_fmamk_f32 v130, v130, 0x3a800000, v231
	v_rsq_f32_e32 v160, v130
	s_nop 1
	ds_write_b32 v212, v160 offset:512
	s_nop 1
	v_pk_mul_f32 v[62:63], v[62:63], v[160:161] op_sel_hi:[1,0]
	v_pk_mul_f32 v[64:65], v[64:65], v[160:161] op_sel_hi:[1,0]
	v_pk_mul_f32 v[58:59], v[58:59], v[160:161] op_sel_hi:[1,0]
	v_pk_mul_f32 v[60:61], v[60:61], v[160:161] op_sel_hi:[1,0]
	v_pk_mul_f32 v[54:55], v[54:55], v[160:161] op_sel_hi:[1,0]
	v_pk_mul_f32 v[56:57], v[56:57], v[160:161] op_sel_hi:[1,0]
	v_pk_mul_f32 v[50:51], v[50:51], v[160:161] op_sel_hi:[1,0]
	v_pk_mul_f32 v[52:53], v[52:53], v[160:161] op_sel_hi:[1,0]
	v_add_f32_e32 v130, v199, v198
	v_add_f32_e32 v131, v200, v201
	s_nop 0
	v_add_f32_e32 v130, v130, v131
	v_mov_b32_e32 v131, v130
	s_nop 1
	v_permlane16_swap_b32 v131, v130
	s_waitcnt lgkmcnt(0)
	v_add_f32_e32 v130, v130, v131
	v_mov_b32_e32 v131, v130
	s_nop 1
	v_permlane32_swap_b32 v131, v130
	s_waitcnt lgkmcnt(0)
	v_add_f32_e32 v130, v130, v131
	v_fmamk_f32 v130, v130, 0x3a800000, v231
	v_rsq_f32_e32 v154, v130
	s_nop 1
	ds_write_b32 v212, v154 offset:576
	s_nop 1
	v_pk_mul_f32 v[46:47], v[46:47], v[154:155] op_sel_hi:[1,0]
	v_pk_mul_f32 v[48:49], v[48:49], v[154:155] op_sel_hi:[1,0]
	v_pk_mul_f32 v[42:43], v[42:43], v[154:155] op_sel_hi:[1,0]
	v_pk_mul_f32 v[44:45], v[44:45], v[154:155] op_sel_hi:[1,0]
	v_pk_mul_f32 v[38:39], v[38:39], v[154:155] op_sel_hi:[1,0]
	v_pk_mul_f32 v[40:41], v[40:41], v[154:155] op_sel_hi:[1,0]
	v_pk_mul_f32 v[34:35], v[34:35], v[154:155] op_sel_hi:[1,0]
	v_pk_mul_f32 v[36:37], v[36:37], v[154:155] op_sel_hi:[1,0]
	v_add_f32_e32 v130, v203, v202
	v_add_f32_e32 v131, v204, v205
	v_add_u32_e32 v148, 0xb0, v156
	v_add_f32_e32 v130, v130, v131
	v_mov_b32_e32 v131, v130
	s_nop 1
	v_permlane16_swap_b32 v131, v130
	v_ashrrev_i32_e32 v149, 31, v148
	s_waitcnt lgkmcnt(0)
	v_add_f32_e32 v130, v130, v131
	v_mov_b32_e32 v131, v130
	s_nop 1
	v_permlane32_swap_b32 v131, v130
	s_waitcnt lgkmcnt(0)
	v_add_f32_e32 v130, v130, v131
	v_fmamk_f32 v130, v130, 0x3a800000, v231
	v_rsq_f32_e32 v150, v130
	s_nop 1
	ds_write_b32 v212, v150 offset:640
	s_nop 1
	v_pk_mul_f32 v[30:31], v[30:31], v[150:151] op_sel_hi:[1,0]
	v_pk_mul_f32 v[32:33], v[32:33], v[150:151] op_sel_hi:[1,0]
	v_pk_mul_f32 v[26:27], v[26:27], v[150:151] op_sel_hi:[1,0]
	v_pk_mul_f32 v[28:29], v[28:29], v[150:151] op_sel_hi:[1,0]
	v_pk_mul_f32 v[22:23], v[22:23], v[150:151] op_sel_hi:[1,0]
	v_pk_mul_f32 v[24:25], v[24:25], v[150:151] op_sel_hi:[1,0]
	v_pk_mul_f32 v[18:19], v[18:19], v[150:151] op_sel_hi:[1,0]
	v_pk_mul_f32 v[20:21], v[20:21], v[150:151] op_sel_hi:[1,0]
	v_add_f32_e32 v130, v207, v206
	v_add_f32_e32 v131, v208, v209
	v_mov_b64_e32 v[132:133], s[16:17]
	v_add_f32_e32 v130, v130, v131
	v_mov_b32_e32 v131, v130
	s_nop 1
	v_permlane16_swap_b32 v131, v130
	v_mad_i64_i32 v[180:181], s[24:25], v156, s96, v[132:133]
	s_waitcnt lgkmcnt(0)
	v_add_f32_e32 v130, v130, v131
	v_mov_b32_e32 v131, v130
	s_nop 1
	v_permlane32_swap_b32 v131, v130
	s_waitcnt lgkmcnt(0)
	v_add_f32_e32 v130, v130, v131
	v_lshl_or_b32 v131, s51, 8, v155
	v_ashrrev_i32_e32 v178, 1, v131
	v_mul_f32_e32 v131, 0xbfb8aa3b, v122
	v_exp_f32_e32 v131, v131
	v_ashrrev_i32_e32 v179, 31, v178
	v_lshlrev_b64 v[156:157], 1, v[178:179]
	v_lshl_add_u64 v[178:179], v[180:181], 0, v[156:157]
	v_add_f32_e32 v131, 1.0, v131
	v_rcp_f32_e32 v131, v131
	v_fmamk_f32 v130, v130, 0x3a800000, v231
	v_rsq_f32_e32 v130, v130
	s_nop 1
	ds_write_b32 v212, v130 offset:704
	s_branch .Lmy_rs_join_3
.Lmy_rs_cached_3:
	v_lshlrev_b32_e32 v212, 2, v1
	v_add_u32_e32 v212, 0x21000, v212
	ds_read_b32 v182, v212
	ds_read_b32 v186, v212 offset:64
	ds_read_b32 v190, v212 offset:128
	ds_read_b32 v194, v212 offset:192
	ds_read_b32 v198, v212 offset:512
	ds_read_b32 v202, v212 offset:576
	ds_read_b32 v206, v212 offset:640
	ds_read_b32 v210, v212 offset:704
	s_waitcnt lgkmcnt(0)
	v_lshl_add_u32 v156, s52, 8, v1
	v_ashrrev_i32_e32 v157, 31, v156
	v_lshlrev_b64 v[130:131], 6, v[156:157]
	v_lshl_add_u64 v[130:131], v[142:143], 0, v[130:131]
	v_or_b32_e32 v174, 16, v156
	v_ashrrev_i32_e32 v175, 31, v174
	v_or_b32_e32 v170, 32, v156
	v_ashrrev_i32_e32 v171, 31, v170
	v_or_b32_e32 v166, 48, v156
	v_ashrrev_i32_e32 v167, 31, v166
	v_add_u32_e32 v162, 0x80, v156
	v_ashrrev_i32_e32 v163, 31, v162
	v_add_u32_e32 v158, 0x90, v156
	v_ashrrev_i32_e32 v159, 31, v158
	v_add_u32_e32 v152, 0xa0, v156
	v_ashrrev_i32_e32 v153, 31, v152
	s_and_b64 vcc, exec, s[4:5]
	v_mov_b32_e32 v148, v131
	v_mov_b32_e32 v149, v132
	v_mov_b32_e32 v131, v133
	v_pk_add_f32 v[130:131], v[148:149], v[130:131]
	s_nop 0
	v_add_f32_e32 v130, v130, v131
	v_mov_b32_e32 v131, v130
	s_nop 1
	v_permlane16_swap_b32 v131, v130
	s_waitcnt lgkmcnt(0)
	v_add_f32_e32 v130, v130, v131
	v_mov_b32_e32 v131, v130
	s_nop 1
	v_permlane32_swap_b32 v131, v130
	s_waitcnt lgkmcnt(0)
	v_add_f32_e32 v130, v130, v131
	v_fmamk_f32 v130, v130, 0x3a800000, v231
	v_mov_b32_e32 v176, v182
	s_nop 1
	v_pk_mul_f32 v[122:123], v[122:123], v[176:177] op_sel_hi:[1,0]
	v_pk_mul_f32 v[124:125], v[124:125], v[176:177] op_sel_hi:[1,0]
	v_pk_mul_f32 v[126:127], v[126:127], v[176:177] op_sel_hi:[1,0]
	v_pk_mul_f32 v[128:129], v[128:129], v[176:177] op_sel_hi:[1,0]
	v_pk_mul_f32 v[118:119], v[118:119], v[176:177] op_sel_hi:[1,0]
	v_pk_mul_f32 v[120:121], v[120:121], v[176:177] op_sel_hi:[1,0]
	v_pk_mul_f32 v[114:115], v[114:115], v[176:177] op_sel_hi:[1,0]
	v_pk_mul_f32 v[116:117], v[116:117], v[176:177] op_sel_hi:[1,0]
	v_add_f32_e32 v130, v183, v182
	v_add_f32_e32 v131, v184, v185
	s_nop 0
	v_add_f32_e32 v130, v130, v131
	v_mov_b32_e32 v131, v130
	s_nop 1
	v_permlane16_swap_b32 v131, v130
	s_waitcnt lgkmcnt(0)
; __device__ __forceinline__ float row_rstd16_coop(const float* ssq, int row, int fq, float inv_n) {
;     const f32x4 a = *(const f32x4*)(ssq + (size_t)row * 16 + fq * 4);
;     float s = (a[0] + a[1]) + (a[2] + a[3]);
;     s += __shfl_xor(s, 16); s += __shfl_xor(s, 32);
;     return __builtin_amdgcn_rsqf(s * inv_n + EPS);
; }
;     __device__ __forceinline__ void operator()(const f32x4 (&acc)[2][2][4][2], const Unit& u, int wr, int wc, int fr, int fq) const {
;         const int row0 = u.pm * BM + wr * 64 + fr, col0 = u.pn * BM + wc * 32 + 8 * fq;
;         float rsv[2][4];
; #pragma unroll
;         for (int ai = 0; ai < 2; ++ai) {
; #pragma unroll
;             for (int m = 0; m < 4; ++m) rsv[ai][m] = ssq ? row_rstd16_coop(ssq, row0 + ai * HALF + m * 16, fq, 1.0f / 1024.0f) : 1.0f;
;         }
; #pragma unroll
;         for (int ai = 0; ai < 2; ++ai)
; #pragma unroll
;             for (int m = 0; m < 4; ++m) {
;                 const int row = row0 + ai * HALF + m * 16;
;                 const float rs = rsv[ai][m];
	v_add_f32_e32 v130, v130, v131
	v_mov_b32_e32 v131, v130
	s_nop 1
	v_permlane32_swap_b32 v131, v130
	s_waitcnt lgkmcnt(0)
	v_add_f32_e32 v130, v130, v131
	v_fmamk_f32 v130, v130, 0x3a800000, v231
	v_mov_b32_e32 v172, v186
	s_nop 1
	v_pk_mul_f32 v[110:111], v[110:111], v[172:173] op_sel_hi:[1,0]
	v_pk_mul_f32 v[112:113], v[112:113], v[172:173] op_sel_hi:[1,0]
	v_pk_mul_f32 v[106:107], v[106:107], v[172:173] op_sel_hi:[1,0]
	v_pk_mul_f32 v[108:109], v[108:109], v[172:173] op_sel_hi:[1,0]
	v_pk_mul_f32 v[102:103], v[102:103], v[172:173] op_sel_hi:[1,0]
	v_pk_mul_f32 v[104:105], v[104:105], v[172:173] op_sel_hi:[1,0]
	v_pk_mul_f32 v[98:99], v[98:99], v[172:173] op_sel_hi:[1,0]
	v_pk_mul_f32 v[100:101], v[100:101], v[172:173] op_sel_hi:[1,0]
	v_add_f32_e32 v130, v187, v186
	v_add_f32_e32 v131, v188, v189
	s_nop 0
	v_add_f32_e32 v130, v130, v131
	v_mov_b32_e32 v131, v130
	s_nop 1
	v_permlane16_swap_b32 v131, v130
	s_waitcnt lgkmcnt(0)
	v_add_f32_e32 v130, v130, v131
	v_mov_b32_e32 v131, v130
	s_nop 1
	v_permlane32_swap_b32 v131, v130
	s_waitcnt lgkmcnt(0)
	v_add_f32_e32 v130, v130, v131
	v_fmamk_f32 v130, v130, 0x3a800000, v231
	v_mov_b32_e32 v168, v190
	s_nop 1
	v_pk_mul_f32 v[94:95], v[94:95], v[168:169] op_sel_hi:[1,0]
	v_pk_mul_f32 v[96:97], v[96:97], v[168:169] op_sel_hi:[1,0]
	v_pk_mul_f32 v[90:91], v[90:91], v[168:169] op_sel_hi:[1,0]
	v_pk_mul_f32 v[92:93], v[92:93], v[168:169] op_sel_hi:[1,0]
	v_pk_mul_f32 v[86:87], v[86:87], v[168:169] op_sel_hi:[1,0]
	v_pk_mul_f32 v[88:89], v[88:89], v[168:169] op_sel_hi:[1,0]
	v_pk_mul_f32 v[82:83], v[82:83], v[168:169] op_sel_hi:[1,0]
	v_pk_mul_f32 v[84:85], v[84:85], v[168:169] op_sel_hi:[1,0]
	v_add_f32_e32 v130, v191, v190
	v_add_f32_e32 v131, v192, v193
	s_nop 0
	v_add_f32_e32 v130, v130, v131
	v_mov_b32_e32 v131, v130
	s_nop 1
	v_permlane16_swap_b32 v131, v130
	s_waitcnt lgkmcnt(0)
	v_add_f32_e32 v130, v130, v131
	v_mov_b32_e32 v131, v130
	s_nop 1
	v_permlane32_swap_b32 v131, v130
	s_waitcnt lgkmcnt(0)
	v_add_f32_e32 v130, v130, v131
	v_fmamk_f32 v130, v130, 0x3a800000, v231
	v_mov_b32_e32 v164, v194
	s_nop 1
	v_pk_mul_f32 v[78:79], v[78:79], v[164:165] op_sel_hi:[1,0]
	v_pk_mul_f32 v[80:81], v[80:81], v[164:165] op_sel_hi:[1,0]
	v_pk_mul_f32 v[74:75], v[74:75], v[164:165] op_sel_hi:[1,0]
	v_pk_mul_f32 v[76:77], v[76:77], v[164:165] op_sel_hi:[1,0]
	v_pk_mul_f32 v[70:71], v[70:71], v[164:165] op_sel_hi:[1,0]
	v_pk_mul_f32 v[72:73], v[72:73], v[164:165] op_sel_hi:[1,0]
	v_pk_mul_f32 v[66:67], v[66:67], v[164:165] op_sel_hi:[1,0]
	v_pk_mul_f32 v[68:69], v[68:69], v[164:165] op_sel_hi:[1,0]
	v_add_f32_e32 v130, v195, v194
	v_add_f32_e32 v131, v196, v197
	s_nop 0
	v_add_f32_e32 v130, v130, v131
	v_mov_b32_e32 v131, v130
	s_nop 1
	v_permlane16_swap_b32 v131, v130
	s_waitcnt lgkmcnt(0)
	v_add_f32_e32 v130, v130, v131
	v_mov_b32_e32 v131, v130
	s_nop 1
	v_permlane32_swap_b32 v131, v130
	s_waitcnt lgkmcnt(0)
	v_add_f32_e32 v130, v130, v131
	v_fmamk_f32 v130, v130, 0x3a800000, v231
	v_mov_b32_e32 v160, v198
	s_nop 1
	v_pk_mul_f32 v[62:63], v[62:63], v[160:161] op_sel_hi:[1,0]
	v_pk_mul_f32 v[64:65], v[64:65], v[160:161] op_sel_hi:[1,0]
	v_pk_mul_f32 v[58:59], v[58:59], v[160:161] op_sel_hi:[1,0]
	v_pk_mul_f32 v[60:61], v[60:61], v[160:161] op_sel_hi:[1,0]
	v_pk_mul_f32 v[54:55], v[54:55], v[160:161] op_sel_hi:[1,0]
	v_pk_mul_f32 v[56:57], v[56:57], v[160:161] op_sel_hi:[1,0]
	v_pk_mul_f32 v[50:51], v[50:51], v[160:161] op_sel_hi:[1,0]
	v_pk_mul_f32 v[52:53], v[52:53], v[160:161] op_sel_hi:[1,0]
	v_add_f32_e32 v130, v199, v198
	v_add_f32_e32 v131, v200, v201
	s_nop 0
	v_add_f32_e32 v130, v130, v131
	v_mov_b32_e32 v131, v130
	s_nop 1
	v_permlane16_swap_b32 v131, v130
	s_waitcnt lgkmcnt(0)
	v_add_f32_e32 v130, v130, v131
	v_mov_b32_e32 v131, v130
	s_nop 1
	v_permlane32_swap_b32 v131, v130
	s_waitcnt lgkmcnt(0)
	v_add_f32_e32 v130, v130, v131
	v_fmamk_f32 v130, v130, 0x3a800000, v231
	v_mov_b32_e32 v154, v202
	s_nop 1
	v_pk_mul_f32 v[46:47], v[46:47], v[154:155] op_sel_hi:[1,0]
	v_pk_mul_f32 v[48:49], v[48:49], v[154:155] op_sel_hi:[1,0]
	v_pk_mul_f32 v[42:43], v[42:43], v[154:155] op_sel_hi:[1,0]
	v_pk_mul_f32 v[44:45], v[44:45], v[154:155] op_sel_hi:[1,0]
	v_pk_mul_f32 v[38:39], v[38:39], v[154:155] op_sel_hi:[1,0]
	v_pk_mul_f32 v[40:41], v[40:41], v[154:155] op_sel_hi:[1,0]
	v_pk_mul_f32 v[34:35], v[34:35], v[154:155] op_sel_hi:[1,0]
	v_pk_mul_f32 v[36:37], v[36:37], v[154:155] op_sel_hi:[1,0]
	v_add_f32_e32 v130, v203, v202
	v_add_f32_e32 v131, v204, v205
	v_add_u32_e32 v148, 0xb0, v156
	v_add_f32_e32 v130, v130, v131
	v_mov_b32_e32 v131, v130
	s_nop 1
	v_permlane16_swap_b32 v131, v130
	v_ashrrev_i32_e32 v149, 31, v148
	s_waitcnt lgkmcnt(0)
	v_add_f32_e32 v130, v130, v131
	v_mov_b32_e32 v131, v130
	s_nop 1
	v_permlane32_swap_b32 v131, v130
	s_waitcnt lgkmcnt(0)
	v_add_f32_e32 v130, v130, v131
	v_fmamk_f32 v130, v130, 0x3a800000, v231
	v_mov_b32_e32 v150, v206
	s_nop 1
	v_pk_mul_f32 v[30:31], v[30:31], v[150:151] op_sel_hi:[1,0]
	v_pk_mul_f32 v[32:33], v[32:33], v[150:151] op_sel_hi:[1,0]
	v_pk_mul_f32 v[26:27], v[26:27], v[150:151] op_sel_hi:[1,0]
	v_pk_mul_f32 v[28:29], v[28:29], v[150:151] op_sel_hi:[1,0]
	v_pk_mul_f32 v[22:23], v[22:23], v[150:151] op_sel_hi:[1,0]
	v_pk_mul_f32 v[24:25], v[24:25], v[150:151] op_sel_hi:[1,0]
	v_pk_mul_f32 v[18:19], v[18:19], v[150:151] op_sel_hi:[1,0]
	v_pk_mul_f32 v[20:21], v[20:21], v[150:151] op_sel_hi:[1,0]
	v_add_f32_e32 v130, v207, v206
	v_add_f32_e32 v131, v208, v209
	v_mov_b64_e32 v[132:133], s[16:17]
	v_add_f32_e32 v130, v130, v131
	v_mov_b32_e32 v131, v130
	s_nop 1
	v_permlane16_swap_b32 v131, v130
	v_mad_i64_i32 v[180:181], s[24:25], v156, s96, v[132:133]
	s_waitcnt lgkmcnt(0)
	v_add_f32_e32 v130, v130, v131
	v_mov_b32_e32 v131, v130
	s_nop 1
	v_permlane32_swap_b32 v131, v130
	s_waitcnt lgkmcnt(0)
	v_add_f32_e32 v130, v130, v131
	v_lshl_or_b32 v131, s51, 8, v155
	v_ashrrev_i32_e32 v178, 1, v131
	v_mul_f32_e32 v131, 0xbfb8aa3b, v122
	v_exp_f32_e32 v131, v131
	v_ashrrev_i32_e32 v179, 31, v178
	v_lshlrev_b64 v[156:157], 1, v[178:179]
	v_lshl_add_u64 v[178:179], v[180:181], 0, v[156:157]
	v_add_f32_e32 v131, 1.0, v131
	v_rcp_f32_e32 v131, v131
	v_fmamk_f32 v130, v130, 0x3a800000, v231
	v_mov_b32_e32 v130, v210
; __device__ __forceinline__ unsigned cvt_pk_bf16(float lo, float hi) { unsigned r; asm volatile("v_cvt_pk_bf16_f32 %0, %1, %2" : "=v"(r) : "v"(lo), "v"(hi)); return r; }
;     __device__ __forceinline__ static float sg(float g, float uu) { return g * __builtin_amdgcn_rcpf(1.0f + __builtin_amdgcn_exp2f(-1.4426950408889634f * g)) * uu; }
;     __device__ __forceinline__ void operator()(const f32x4 (&acc)[2][2][4][2], const Unit& u, int wr, int wc, int fr, int fq) const {
;         const int row0 = u.pm * BM + wr * 64 + fr, col0 = u.pn * BM + wc * 32 + 8 * fq;
;         float rsv[2][4];
; #pragma unroll
;         for (int ai = 0; ai < 2; ++ai) {
; #pragma unroll
;             for (int m = 0; m < 4; ++m) rsv[ai][m] = row_rstd16_coop(ssq, row0 + ai * HALF + m * 16, fq, 1.0f / 1024.0f);
;         }
; #pragma unroll
;         for (int ai = 0; ai < 2; ++ai)
; #pragma unroll
;             for (int m = 0; m < 4; ++m) {
;                 const int row = row0 + ai * HALF + m * 16;
;                 const float rs = rsv[ai][m];
;                 bf16_t* rowp = H + (size_t)row * ldh + (col0 >> 1);
; #pragma unroll
;                 for (int bj = 0; bj < 2; ++bj) {
;                     const f32x4 v0 = acc[ai][bj][m][0] * rs, v1 = acc[ai][bj][m][1] * rs;
;                     u32x2 w; w.x = cvt_pk_bf16(sg(v0[0], v0[1]), sg(v0[2], v0[3])); w.y = cvt_pk_bf16(sg(v1[0], v1[1]), sg(v1[2], v1[3]));
;                     *(u32x2*)(rowp + bj * (HALF / 2)) = w;
;                 }
;             }
.Lmy_rs_join_3:
	v_mul_f32_e32 v122, v122, v131
	v_mul_f32_e32 v122, v123, v122
	v_mul_f32_e32 v123, 0xbfb8aa3b, v124
	v_exp_f32_e32 v123, v123
	v_pk_mul_f32 v[14:15], v[14:15], v[130:131] op_sel_hi:[1,0]
	v_pk_mul_f32 v[16:17], v[16:17], v[130:131] op_sel_hi:[1,0]
	v_pk_mul_f32 v[10:11], v[10:11], v[130:131] op_sel_hi:[1,0]
	v_add_f32_e32 v123, 1.0, v123
	v_rcp_f32_e32 v123, v123
	v_pk_mul_f32 v[12:13], v[12:13], v[130:131] op_sel_hi:[1,0]
	v_pk_mul_f32 v[6:7], v[6:7], v[130:131] op_sel_hi:[1,0]
	v_pk_mul_f32 v[8:9], v[8:9], v[130:131] op_sel_hi:[1,0]
	v_mul_f32_e32 v123, v124, v123
	v_mul_f32_e32 v123, v125, v123
	v_cvt_pk_bf16_f32 v122, v122, v123
	v_mul_f32_e32 v123, 0xbfb8aa3b, v126
	v_exp_f32_e32 v123, v123
	v_mul_f32_e32 v124, 0xbfb8aa3b, v128
	v_exp_f32_e32 v124, v124
	v_pk_mul_f32 v[2:3], v[2:3], v[130:131] op_sel_hi:[1,0]
	v_add_f32_e32 v123, 1.0, v123
	v_rcp_f32_e32 v123, v123
	v_add_f32_e32 v124, 1.0, v124
	v_rcp_f32_e32 v124, v124
	v_pk_mul_f32 v[4:5], v[4:5], v[130:131] op_sel_hi:[1,0]
	v_mul_f32_e32 v123, v126, v123
	v_mul_f32_e32 v123, v127, v123
	v_mul_f32_e32 v124, v128, v124
	v_mul_f32_e32 v124, v129, v124
	v_cvt_pk_bf16_f32 v123, v123, v124
	global_store_dwordx2 v[178:179], v[122:123], off
	v_mul_f32_e32 v122, 0xbfb8aa3b, v118
	v_exp_f32_e32 v122, v122
	s_nop 0
	v_add_f32_e32 v122, 1.0, v122
	v_rcp_f32_e32 v122, v122
	s_nop 0
	v_mul_f32_e32 v118, v118, v122
	v_mul_f32_e32 v118, v119, v118
	v_mul_f32_e32 v119, 0xbfb8aa3b, v120
	v_exp_f32_e32 v119, v119
	s_nop 0
	v_add_f32_e32 v119, 1.0, v119
	v_rcp_f32_e32 v119, v119
	s_nop 0
	v_mul_f32_e32 v119, v120, v119
	v_mul_f32_e32 v119, v121, v119
	v_cvt_pk_bf16_f32 v118, v118, v119
	v_mul_f32_e32 v119, 0xbfb8aa3b, v114
	v_exp_f32_e32 v119, v119
	s_nop 0
	v_add_f32_e32 v119, 1.0, v119
	v_rcp_f32_e32 v119, v119
	s_nop 0
	v_mul_f32_e32 v114, v114, v119
	v_mul_f32_e32 v114, v115, v114
	v_mul_f32_e32 v115, 0xbfb8aa3b, v116
	v_exp_f32_e32 v115, v115
	s_nop 0
	v_add_f32_e32 v115, 1.0, v115
	v_rcp_f32_e32 v115, v115
	s_nop 0
	v_mul_f32_e32 v115, v116, v115
	v_mul_f32_e32 v116, 0xbfb8aa3b, v110
	v_exp_f32_e32 v116, v116
	v_mul_f32_e32 v115, v117, v115
	v_cvt_pk_bf16_f32 v119, v114, v115
	global_store_dwordx2 v[178:179], v[118:119], off offset:128
	v_add_f32_e32 v116, 1.0, v116
	v_rcp_f32_e32 v116, v116
	v_mad_i64_i32 v[114:115], s[24:25], v174, s96, v[132:133]
	v_lshl_add_u64 v[114:115], v[114:115], 0, v[156:157]
	v_mul_f32_e32 v110, v110, v116
	v_mul_f32_e32 v110, v111, v110
	v_mul_f32_e32 v111, 0xbfb8aa3b, v112
	v_exp_f32_e32 v111, v111
	s_nop 0
	v_add_f32_e32 v111, 1.0, v111
	v_rcp_f32_e32 v111, v111
	s_nop 0
	v_mul_f32_e32 v111, v112, v111
	v_mul_f32_e32 v111, v113, v111
	v_cvt_pk_bf16_f32 v110, v110, v111
	v_mul_f32_e32 v111, 0xbfb8aa3b, v106
	v_exp_f32_e32 v111, v111
	s_nop 0
	v_add_f32_e32 v111, 1.0, v111
	v_rcp_f32_e32 v111, v111
	s_nop 0
	v_mul_f32_e32 v106, v106, v111
	v_mul_f32_e32 v106, v107, v106
	v_mul_f32_e32 v107, 0xbfb8aa3b, v108
	v_exp_f32_e32 v107, v107
	s_nop 0
	v_add_f32_e32 v107, 1.0, v107
	v_rcp_f32_e32 v107, v107
	s_nop 0
	v_mul_f32_e32 v107, v108, v107
	v_mul_f32_e32 v107, v109, v107
	v_cvt_pk_bf16_f32 v111, v106, v107
	v_mul_f32_e32 v106, 0xbfb8aa3b, v102
	v_exp_f32_e32 v106, v106
	global_store_dwordx2 v[114:115], v[110:111], off
	v_add_f32_e32 v106, 1.0, v106
	v_rcp_f32_e32 v106, v106
	s_nop 0
	v_mul_f32_e32 v102, v102, v106
	v_mul_f32_e32 v102, v103, v102
	v_mul_f32_e32 v103, 0xbfb8aa3b, v104
	v_exp_f32_e32 v103, v103
	s_nop 0
	v_add_f32_e32 v103, 1.0, v103
	v_rcp_f32_e32 v103, v103
	s_nop 0
	v_mul_f32_e32 v103, v104, v103
	v_mul_f32_e32 v103, v105, v103
	v_cvt_pk_bf16_f32 v102, v102, v103
	v_mul_f32_e32 v103, 0xbfb8aa3b, v98
	v_exp_f32_e32 v103, v103
	s_nop 0
	v_add_f32_e32 v103, 1.0, v103
	v_rcp_f32_e32 v103, v103
	s_nop 0
	v_mul_f32_e32 v98, v98, v103
	v_mul_f32_e32 v98, v99, v98
	v_mul_f32_e32 v99, 0xbfb8aa3b, v100
	v_exp_f32_e32 v99, v99
	s_nop 0
	v_add_f32_e32 v99, 1.0, v99
	v_rcp_f32_e32 v99, v99
	s_nop 0
	v_mul_f32_e32 v99, v100, v99
	v_mul_f32_e32 v100, 0xbfb8aa3b, v94
	v_exp_f32_e32 v100, v100
	v_mul_f32_e32 v99, v101, v99
	v_cvt_pk_bf16_f32 v103, v98, v99
	global_store_dwordx2 v[114:115], v[102:103], off offset:128
	v_add_f32_e32 v100, 1.0, v100
	v_rcp_f32_e32 v100, v100
	v_mad_i64_i32 v[98:99], s[24:25], v170, s96, v[132:133]
	v_lshl_add_u64 v[98:99], v[98:99], 0, v[156:157]
	v_mul_f32_e32 v94, v94, v100
	v_mul_f32_e32 v94, v95, v94
	v_mul_f32_e32 v95, 0xbfb8aa3b, v96
	v_exp_f32_e32 v95, v95
	s_nop 0
	v_add_f32_e32 v95, 1.0, v95
	v_rcp_f32_e32 v95, v95
	s_nop 0
	v_mul_f32_e32 v95, v96, v95
	v_mul_f32_e32 v95, v97, v95
	v_cvt_pk_bf16_f32 v94, v94, v95
	v_mul_f32_e32 v95, 0xbfb8aa3b, v90
	v_exp_f32_e32 v95, v95
	s_nop 0
	v_add_f32_e32 v95, 1.0, v95
	v_rcp_f32_e32 v95, v95
	s_nop 0
	v_mul_f32_e32 v90, v90, v95
	v_mul_f32_e32 v90, v91, v90
	v_mul_f32_e32 v91, 0xbfb8aa3b, v92
	v_exp_f32_e32 v91, v91
	s_nop 0
	v_add_f32_e32 v91, 1.0, v91
	v_rcp_f32_e32 v91, v91
	s_nop 0
	v_mul_f32_e32 v91, v92, v91
	v_mul_f32_e32 v91, v93, v91
	v_cvt_pk_bf16_f32 v95, v90, v91
	v_mul_f32_e32 v90, 0xbfb8aa3b, v86
	v_exp_f32_e32 v90, v90
	global_store_dwordx2 v[98:99], v[94:95], off
	v_add_f32_e32 v90, 1.0, v90
	v_rcp_f32_e32 v90, v90
	s_nop 0
	v_mul_f32_e32 v86, v86, v90
	v_mul_f32_e32 v86, v87, v86
	v_mul_f32_e32 v87, 0xbfb8aa3b, v88
	v_exp_f32_e32 v87, v87
	s_nop 0
	v_add_f32_e32 v87, 1.0, v87
	v_rcp_f32_e32 v87, v87
	s_nop 0
	v_mul_f32_e32 v87, v88, v87
	v_mul_f32_e32 v87, v89, v87
	v_cvt_pk_bf16_f32 v86, v86, v87
	v_mul_f32_e32 v87, 0xbfb8aa3b, v82
	v_exp_f32_e32 v87, v87
	s_nop 0
	v_add_f32_e32 v87, 1.0, v87
	v_rcp_f32_e32 v87, v87
	s_nop 0
	v_mul_f32_e32 v82, v82, v87
; __device__ __forceinline__ unsigned cvt_pk_bf16(float lo, float hi) { unsigned r; asm volatile("v_cvt_pk_bf16_f32 %0, %1, %2" : "=v"(r) : "v"(lo), "v"(hi)); return r; }
;     __device__ __forceinline__ static float sg(float g, float uu) { return g * __builtin_amdgcn_rcpf(1.0f + __builtin_amdgcn_exp2f(-1.4426950408889634f * g)) * uu; }
;     __device__ __forceinline__ void operator()(const f32x4 (&acc)[2][2][4][2], const Unit& u, int wr, int wc, int fr, int fq) const {
;     ...
;         for (int ai = 0; ai < 2; ++ai)
; #pragma unroll
;             for (int m = 0; m < 4; ++m) {
;                 const int row = row0 + ai * HALF + m * 16;
;                 const float rs = rsv[ai][m];
;                 bf16_t* rowp = H + (size_t)row * ldh + (col0 >> 1);
; #pragma unroll
;                 for (int bj = 0; bj < 2; ++bj) {
;                     const f32x4 v0 = acc[ai][bj][m][0] * rs, v1 = acc[ai][bj][m][1] * rs;
;                     u32x2 w; w.x = cvt_pk_bf16(sg(v0[0], v0[1]), sg(v0[2], v0[3])); w.y = cvt_pk_bf16(sg(v1[0], v1[1]), sg(v1[2], v1[3]));
;                     *(u32x2*)(rowp + bj * (HALF / 2)) = w;
;                 }
;             }
	v_mul_f32_e32 v82, v83, v82
	v_mul_f32_e32 v83, 0xbfb8aa3b, v84
	v_exp_f32_e32 v83, v83
	s_nop 0
	v_add_f32_e32 v83, 1.0, v83
	v_rcp_f32_e32 v83, v83
	s_nop 0
	v_mul_f32_e32 v83, v84, v83
	v_mul_f32_e32 v84, 0xbfb8aa3b, v78
	v_exp_f32_e32 v84, v84
	v_mul_f32_e32 v83, v85, v83
	v_cvt_pk_bf16_f32 v87, v82, v83
	global_store_dwordx2 v[98:99], v[86:87], off offset:128
	v_add_f32_e32 v84, 1.0, v84
	v_rcp_f32_e32 v84, v84
	v_mad_i64_i32 v[82:83], s[24:25], v166, s96, v[132:133]
	v_lshl_add_u64 v[82:83], v[82:83], 0, v[156:157]
	v_mul_f32_e32 v78, v78, v84
	v_mul_f32_e32 v78, v79, v78
	v_mul_f32_e32 v79, 0xbfb8aa3b, v80
	v_exp_f32_e32 v79, v79
	s_nop 0
	v_add_f32_e32 v79, 1.0, v79
	v_rcp_f32_e32 v79, v79
	s_nop 0
	v_mul_f32_e32 v79, v80, v79
	v_mul_f32_e32 v79, v81, v79
	v_cvt_pk_bf16_f32 v78, v78, v79
	v_mul_f32_e32 v79, 0xbfb8aa3b, v74
	v_exp_f32_e32 v79, v79
	s_nop 0
	v_add_f32_e32 v79, 1.0, v79
	v_rcp_f32_e32 v79, v79
	s_nop 0
	v_mul_f32_e32 v74, v74, v79
	v_mul_f32_e32 v74, v75, v74
	v_mul_f32_e32 v75, 0xbfb8aa3b, v76
	v_exp_f32_e32 v75, v75
	s_nop 0
	v_add_f32_e32 v75, 1.0, v75
	v_rcp_f32_e32 v75, v75
	s_nop 0
	v_mul_f32_e32 v75, v76, v75
	v_mul_f32_e32 v75, v77, v75
	v_cvt_pk_bf16_f32 v79, v74, v75
	v_mul_f32_e32 v74, 0xbfb8aa3b, v70
	v_exp_f32_e32 v74, v74
	global_store_dwordx2 v[82:83], v[78:79], off
	v_add_f32_e32 v74, 1.0, v74
	v_rcp_f32_e32 v74, v74
	s_nop 0
	v_mul_f32_e32 v70, v70, v74
	v_mul_f32_e32 v70, v71, v70
	v_mul_f32_e32 v71, 0xbfb8aa3b, v72
	v_exp_f32_e32 v71, v71
	s_nop 0
	v_add_f32_e32 v71, 1.0, v71
	v_rcp_f32_e32 v71, v71
	s_nop 0
	v_mul_f32_e32 v71, v72, v71
	v_mul_f32_e32 v71, v73, v71
	v_cvt_pk_bf16_f32 v70, v70, v71
	v_mul_f32_e32 v71, 0xbfb8aa3b, v66
	v_exp_f32_e32 v71, v71
	s_nop 0
	v_add_f32_e32 v71, 1.0, v71
	v_rcp_f32_e32 v71, v71
	s_nop 0
	v_mul_f32_e32 v66, v66, v71
	v_mul_f32_e32 v66, v67, v66
	v_mul_f32_e32 v67, 0xbfb8aa3b, v68
	v_exp_f32_e32 v67, v67
	s_nop 0
	v_add_f32_e32 v67, 1.0, v67
	v_rcp_f32_e32 v67, v67
	s_nop 0
	v_mul_f32_e32 v67, v68, v67
	v_mul_f32_e32 v68, 0xbfb8aa3b, v62
	v_exp_f32_e32 v68, v68
	v_mul_f32_e32 v67, v69, v67
	v_cvt_pk_bf16_f32 v71, v66, v67
	global_store_dwordx2 v[82:83], v[70:71], off offset:128
	v_add_f32_e32 v68, 1.0, v68
	v_rcp_f32_e32 v68, v68
	v_mad_i64_i32 v[66:67], s[24:25], v162, s96, v[132:133]
	v_lshl_add_u64 v[66:67], v[66:67], 0, v[156:157]
	v_mul_f32_e32 v62, v62, v68
	v_mul_f32_e32 v62, v63, v62
	v_mul_f32_e32 v63, 0xbfb8aa3b, v64
	v_exp_f32_e32 v63, v63
	s_nop 0
	v_add_f32_e32 v63, 1.0, v63
	v_rcp_f32_e32 v63, v63
	s_nop 0
	v_mul_f32_e32 v63, v64, v63
	v_mul_f32_e32 v63, v65, v63
	v_cvt_pk_bf16_f32 v62, v62, v63
	v_mul_f32_e32 v63, 0xbfb8aa3b, v58
	v_exp_f32_e32 v63, v63
	s_nop 0
	v_add_f32_e32 v63, 1.0, v63
	v_rcp_f32_e32 v63, v63
	s_nop 0
	v_mul_f32_e32 v58, v58, v63
	v_mul_f32_e32 v58, v59, v58
	v_mul_f32_e32 v59, 0xbfb8aa3b, v60
	v_exp_f32_e32 v59, v59
	s_nop 0
	v_add_f32_e32 v59, 1.0, v59
	v_rcp_f32_e32 v59, v59
	s_nop 0
	v_mul_f32_e32 v59, v60, v59
	v_mul_f32_e32 v59, v61, v59
	v_cvt_pk_bf16_f32 v63, v58, v59
	v_mul_f32_e32 v58, 0xbfb8aa3b, v54
	v_exp_f32_e32 v58, v58
	global_store_dwordx2 v[66:67], v[62:63], off
	v_add_f32_e32 v58, 1.0, v58
	v_rcp_f32_e32 v58, v58
	s_nop 0
	v_mul_f32_e32 v54, v54, v58
	v_mul_f32_e32 v54, v55, v54
	v_mul_f32_e32 v55, 0xbfb8aa3b, v56
	v_exp_f32_e32 v55, v55
	s_nop 0
	v_add_f32_e32 v55, 1.0, v55
	v_rcp_f32_e32 v55, v55
	s_nop 0
	v_mul_f32_e32 v55, v56, v55
	v_mul_f32_e32 v55, v57, v55
	v_cvt_pk_bf16_f32 v54, v54, v55
	v_mul_f32_e32 v55, 0xbfb8aa3b, v50
	v_exp_f32_e32 v55, v55
	s_nop 0
	v_add_f32_e32 v55, 1.0, v55
	v_rcp_f32_e32 v55, v55
	s_nop 0
	v_mul_f32_e32 v50, v50, v55
	v_mul_f32_e32 v50, v51, v50
	v_mul_f32_e32 v51, 0xbfb8aa3b, v52
	v_exp_f32_e32 v51, v51
	s_nop 0
	v_add_f32_e32 v51, 1.0, v51
	v_rcp_f32_e32 v51, v51
	s_nop 0
	v_mul_f32_e32 v51, v52, v51
	v_mul_f32_e32 v52, 0xbfb8aa3b, v46
	v_exp_f32_e32 v52, v52
	v_mul_f32_e32 v51, v53, v51
	v_cvt_pk_bf16_f32 v55, v50, v51
	global_store_dwordx2 v[66:67], v[54:55], off offset:128
	v_add_f32_e32 v52, 1.0, v52
	v_rcp_f32_e32 v52, v52
	v_mad_i64_i32 v[50:51], s[24:25], v158, s96, v[132:133]
	v_lshl_add_u64 v[50:51], v[50:51], 0, v[156:157]
	v_mul_f32_e32 v46, v46, v52
	v_mul_f32_e32 v46, v47, v46
	v_mul_f32_e32 v47, 0xbfb8aa3b, v48
	v_exp_f32_e32 v47, v47
	s_nop 0
	v_add_f32_e32 v47, 1.0, v47
	v_rcp_f32_e32 v47, v47
	s_nop 0
	v_mul_f32_e32 v47, v48, v47
	v_mul_f32_e32 v47, v49, v47
	v_cvt_pk_bf16_f32 v46, v46, v47
	v_mul_f32_e32 v47, 0xbfb8aa3b, v42
	v_exp_f32_e32 v47, v47
	s_nop 0
	v_add_f32_e32 v47, 1.0, v47
	v_rcp_f32_e32 v47, v47
	s_nop 0
	v_mul_f32_e32 v42, v42, v47
	v_mul_f32_e32 v42, v43, v42
	v_mul_f32_e32 v43, 0xbfb8aa3b, v44
	v_exp_f32_e32 v43, v43
	s_nop 0
	v_add_f32_e32 v43, 1.0, v43
; __device__ __forceinline__ unsigned cvt_pk_bf16(float lo, float hi) { unsigned r; asm volatile("v_cvt_pk_bf16_f32 %0, %1, %2" : "=v"(r) : "v"(lo), "v"(hi)); return r; }
;     __device__ __forceinline__ static float sg(float g, float uu) { return g * __builtin_amdgcn_rcpf(1.0f + __builtin_amdgcn_exp2f(-1.4426950408889634f * g)) * uu; }
;     __device__ __forceinline__ void operator()(const f32x4 (&acc)[2][2][4][2], const Unit& u, int wr, int wc, int fr, int fq) const {
;     ...
;         for (int ai = 0; ai < 2; ++ai)
; #pragma unroll
;             for (int m = 0; m < 4; ++m) {
;                 const int row = row0 + ai * HALF + m * 16;
;                 const float rs = rsv[ai][m];
;                 bf16_t* rowp = H + (size_t)row * ldh + (col0 >> 1);
; #pragma unroll
;                 for (int bj = 0; bj < 2; ++bj) {
;                     const f32x4 v0 = acc[ai][bj][m][0] * rs, v1 = acc[ai][bj][m][1] * rs;
;                     u32x2 w; w.x = cvt_pk_bf16(sg(v0[0], v0[1]), sg(v0[2], v0[3])); w.y = cvt_pk_bf16(sg(v1[0], v1[1]), sg(v1[2], v1[3]));
;                     *(u32x2*)(rowp + bj * (HALF / 2)) = w;
;                 }
;             }
	v_rcp_f32_e32 v43, v43
	s_nop 0
	v_mul_f32_e32 v43, v44, v43
	v_mul_f32_e32 v43, v45, v43
	v_cvt_pk_bf16_f32 v47, v42, v43
	v_mul_f32_e32 v42, 0xbfb8aa3b, v38
	v_exp_f32_e32 v42, v42
	global_store_dwordx2 v[50:51], v[46:47], off
	v_add_f32_e32 v42, 1.0, v42
	v_rcp_f32_e32 v42, v42
	s_nop 0
	v_mul_f32_e32 v38, v38, v42
	v_mul_f32_e32 v38, v39, v38
	v_mul_f32_e32 v39, 0xbfb8aa3b, v40
	v_exp_f32_e32 v39, v39
	s_nop 0
	v_add_f32_e32 v39, 1.0, v39
	v_rcp_f32_e32 v39, v39
	s_nop 0
	v_mul_f32_e32 v39, v40, v39
	v_mul_f32_e32 v39, v41, v39
	v_cvt_pk_bf16_f32 v38, v38, v39
	v_mul_f32_e32 v39, 0xbfb8aa3b, v34
	v_exp_f32_e32 v39, v39
	s_nop 0
	v_add_f32_e32 v39, 1.0, v39
	v_rcp_f32_e32 v39, v39
	s_nop 0
	v_mul_f32_e32 v34, v34, v39
	v_mul_f32_e32 v34, v35, v34
	v_mul_f32_e32 v35, 0xbfb8aa3b, v36
	v_exp_f32_e32 v35, v35
	s_nop 0
	v_add_f32_e32 v35, 1.0, v35
	v_rcp_f32_e32 v35, v35
	s_nop 0
	v_mul_f32_e32 v35, v36, v35
	v_mul_f32_e32 v36, 0xbfb8aa3b, v30
	v_exp_f32_e32 v36, v36
	v_mul_f32_e32 v35, v37, v35
	v_cvt_pk_bf16_f32 v39, v34, v35
	global_store_dwordx2 v[50:51], v[38:39], off offset:128
	v_add_f32_e32 v36, 1.0, v36
	v_rcp_f32_e32 v36, v36
	v_mad_i64_i32 v[34:35], s[24:25], v152, s96, v[132:133]
	v_lshl_add_u64 v[34:35], v[34:35], 0, v[156:157]
	v_mul_f32_e32 v30, v30, v36
	v_mul_f32_e32 v30, v31, v30
	v_mul_f32_e32 v31, 0xbfb8aa3b, v32
	v_exp_f32_e32 v31, v31
	s_nop 0
	v_add_f32_e32 v31, 1.0, v31
	v_rcp_f32_e32 v31, v31
	s_nop 0
	v_mul_f32_e32 v31, v32, v31
	v_mul_f32_e32 v31, v33, v31
	v_cvt_pk_bf16_f32 v30, v30, v31
	v_mul_f32_e32 v31, 0xbfb8aa3b, v26
	v_exp_f32_e32 v31, v31
	s_nop 0
	v_add_f32_e32 v31, 1.0, v31
	v_rcp_f32_e32 v31, v31
	s_nop 0
	v_mul_f32_e32 v26, v26, v31
	v_mul_f32_e32 v26, v27, v26
	v_mul_f32_e32 v27, 0xbfb8aa3b, v28
	v_exp_f32_e32 v27, v27
	s_nop 0
	v_add_f32_e32 v27, 1.0, v27
	v_rcp_f32_e32 v27, v27
	s_nop 0
	v_mul_f32_e32 v27, v28, v27
	v_mul_f32_e32 v27, v29, v27
	v_cvt_pk_bf16_f32 v31, v26, v27
	v_mul_f32_e32 v26, 0xbfb8aa3b, v22
	v_exp_f32_e32 v26, v26
	global_store_dwordx2 v[34:35], v[30:31], off
	v_add_f32_e32 v26, 1.0, v26
	v_rcp_f32_e32 v26, v26
	s_nop 0
	v_mul_f32_e32 v22, v22, v26
	v_mul_f32_e32 v22, v23, v22
	v_mul_f32_e32 v23, 0xbfb8aa3b, v24
	v_exp_f32_e32 v23, v23
	s_nop 0
	v_add_f32_e32 v23, 1.0, v23
	v_rcp_f32_e32 v23, v23
	s_nop 0
	v_mul_f32_e32 v23, v24, v23
	v_mul_f32_e32 v23, v25, v23
	v_cvt_pk_bf16_f32 v22, v22, v23
	v_mul_f32_e32 v23, 0xbfb8aa3b, v18
	v_exp_f32_e32 v23, v23
	s_nop 0
	v_add_f32_e32 v23, 1.0, v23
	v_rcp_f32_e32 v23, v23
	s_nop 0
	v_mul_f32_e32 v18, v18, v23
	v_mul_f32_e32 v18, v19, v18
	v_mul_f32_e32 v19, 0xbfb8aa3b, v20
	v_exp_f32_e32 v19, v19
	s_nop 0
	v_add_f32_e32 v19, 1.0, v19
	v_rcp_f32_e32 v19, v19
	s_nop 0
	v_mul_f32_e32 v19, v20, v19
	v_mul_f32_e32 v20, 0xbfb8aa3b, v14
	v_exp_f32_e32 v20, v20
	v_mul_f32_e32 v19, v21, v19
	v_cvt_pk_bf16_f32 v23, v18, v19
	global_store_dwordx2 v[34:35], v[22:23], off offset:128
	v_add_f32_e32 v20, 1.0, v20
	v_rcp_f32_e32 v20, v20
	v_mad_i64_i32 v[18:19], s[24:25], v148, s96, v[132:133]
	v_lshl_add_u64 v[18:19], v[18:19], 0, v[156:157]
	v_mul_f32_e32 v14, v14, v20
	v_mul_f32_e32 v14, v15, v14
	v_mul_f32_e32 v15, 0xbfb8aa3b, v16
	v_exp_f32_e32 v15, v15
	s_mov_b64 s[24:25], -1
	v_add_f32_e32 v15, 1.0, v15
	v_rcp_f32_e32 v15, v15
	s_nop 0
	v_mul_f32_e32 v15, v16, v15
	v_mul_f32_e32 v15, v17, v15
	v_cvt_pk_bf16_f32 v14, v14, v15
	v_mul_f32_e32 v15, 0xbfb8aa3b, v10
	v_exp_f32_e32 v15, v15
	s_nop 0
	v_add_f32_e32 v15, 1.0, v15
	v_rcp_f32_e32 v15, v15
	s_nop 0
	v_mul_f32_e32 v10, v10, v15
	v_mul_f32_e32 v10, v11, v10
	v_mul_f32_e32 v11, 0xbfb8aa3b, v12
	v_exp_f32_e32 v11, v11
	s_nop 0
	v_add_f32_e32 v11, 1.0, v11
	v_rcp_f32_e32 v11, v11
	s_nop 0
	v_mul_f32_e32 v11, v12, v11
	v_mul_f32_e32 v11, v13, v11
	v_cvt_pk_bf16_f32 v15, v10, v11
	v_mul_f32_e32 v10, 0xbfb8aa3b, v6
	v_exp_f32_e32 v10, v10
	global_store_dwordx2 v[18:19], v[14:15], off
	v_add_f32_e32 v10, 1.0, v10
	v_rcp_f32_e32 v10, v10
	s_nop 0
	v_mul_f32_e32 v6, v6, v10
	v_mul_f32_e32 v6, v7, v6
	v_mul_f32_e32 v7, 0xbfb8aa3b, v8
	v_exp_f32_e32 v7, v7
	s_nop 0
	v_add_f32_e32 v7, 1.0, v7
	v_rcp_f32_e32 v7, v7
	s_nop 0
	v_mul_f32_e32 v7, v8, v7
	v_mul_f32_e32 v7, v9, v7
	v_cvt_pk_bf16_f32 v6, v6, v7
	v_mul_f32_e32 v7, 0xbfb8aa3b, v2
	v_exp_f32_e32 v7, v7
	s_nop 0
	v_add_f32_e32 v7, 1.0, v7
	v_rcp_f32_e32 v7, v7
	s_nop 0
	v_mul_f32_e32 v2, v2, v7
	v_mul_f32_e32 v2, v3, v2
	v_mul_f32_e32 v3, 0xbfb8aa3b, v4
	v_exp_f32_e32 v3, v3
	s_nop 0
	v_add_f32_e32 v3, 1.0, v3
	v_rcp_f32_e32 v3, v3
	s_nop 0
	v_mul_f32_e32 v3, v4, v3
	v_mul_f32_e32 v3, v5, v3
	v_cvt_pk_bf16_f32 v7, v2, v3
	global_store_dwordx2 v[18:19], v[6:7], off offset:128
	s_cbranch_vccnz .LBB0_4832
	s_andn2_b64 vcc, exec, s[14:15]
	s_cbranch_vccnz .LBB0_4831
	s_barrier
	s_branch .LBB0_4831
